# GEMM K-loops: LDS-DMA addresses from an SGPR base plus per-lane 32-bit offsets and SALU m0 updates (no per-step VALU address math)
# baseline (speedup 1.0000x reference)
.LBB0_210:
	s_mul_hi_i32 s8, s10, 0x3e0f83e1
	s_lshr_b32 s9, s8, 31
	s_ashr_i32 s92, s8, 3
	s_add_i32 s92, s92, s9
	s_lshl_b32 s93, s10, 8
	s_mul_i32 s8, s92, 0xffffdf00
	s_add_i32 s40, s8, s93
	s_andn2_b64 vcc, exec, s[0:1]
	s_mov_b64 s[0:1], -1
	s_cbranch_vccnz .LBB0_246
	v_mov_b32_e32 v20, v190
	s_and_b32 s95, s94, 7
	s_lshl_b32 s10, s95, 8
	v_ashrrev_i32_e32 v16, 3, v20
	v_lshrrev_b32_e32 v21, 4, v20
	v_add_u32_e32 v23, s93, v16
	v_xor_b32_e32 v22, v21, v20
	v_add_u32_e32 v6, 64, v23
	v_mov_b64_e32 v[4:5], s[18:19]
	v_add_u32_e32 v10, 0x80, v23
	v_add_u32_e32 v14, 0xc0, v23
	v_add_u32_e32 v24, s10, v16
	v_mov_b64_e32 v[18:19], s[20:21]
	v_mad_i64_i32 v[0:1], s[0:1], v23, s78, 0
	v_mad_i64_i32 v[2:3], s[0:1], v6, s78, 0
	v_mad_i64_i32 v[6:7], s[0:1], v6, s78, v[4:5]
	v_mad_i64_i32 v[8:9], s[0:1], v10, s78, 0
	v_mad_i64_i32 v[10:11], s[0:1], v10, s78, v[4:5]
	v_mad_i64_i32 v[12:13], s[0:1], v14, s78, 0
	v_mad_i64_i32 v[14:15], s[0:1], v14, s78, v[4:5]
	v_mad_i64_i32 v[16:17], s[0:1], v24, s78, 0
	v_mad_i64_i32 v[18:19], s[0:1], v24, s78, v[18:19]
	v_mad_i64_i32 v[4:5], s[0:1], v23, s78, v[4:5]
	v_lshlrev_b32_e32 v22, 4, v22
	v_lshl_add_u32 v152, v20, 4, 0
	v_and_b32_e32 v176, 0x70, v22
	v_readfirstlane_b32 s0, v152
	v_lshl_add_u64 v[4:5], v[4:5], 0, v[176:177]
	s_mov_b32 m0, s0
	v_lshl_add_u64 v[6:7], v[6:7], 0, v[176:177]
	global_load_lds_dwordx4 v[4:5], off
	v_add_u32_e32 v4, 0x2000, v152
	v_lshl_add_u64 v[10:11], v[10:11], 0, v[176:177]
	v_readfirstlane_b32 s0, v4
	v_add_u32_e32 v4, 0x4000, v152
	s_mov_b32 m0, s0
	v_readfirstlane_b32 s0, v4
	v_add_u32_e32 v4, 0x6000, v152
	global_load_lds_dwordx4 v[6:7], off
	s_mov_b32 m0, s0
	v_readfirstlane_b32 s0, v4
	v_add_u32_e32 v4, 0x8000, v152
	v_lshl_add_u64 v[14:15], v[14:15], 0, v[176:177]
	global_load_lds_dwordx4 v[10:11], off
	s_mov_b32 m0, s0
	v_readfirstlane_b32 s0, v4
	v_lshl_add_u64 v[18:19], v[18:19], 0, v[176:177]
	global_load_lds_dwordx4 v[14:15], off
	s_mov_b32 m0, s0
	s_mov_b64 s[0:1], 0x22000
	v_add_u32_e32 v6, 0xa000, v152
	v_lshl_add_u64 v[4:5], v[18:19], 0, s[0:1]
	v_readfirstlane_b32 s0, v6
	global_load_lds_dwordx4 v[18:19], off
	s_mov_b32 m0, s0
	s_mov_b64 s[0:1], 0x44000
	v_add_u32_e32 v6, 0xc000, v152
	global_load_lds_dwordx4 v[4:5], off
	v_lshl_add_u64 v[4:5], v[18:19], 0, s[0:1]
	v_readfirstlane_b32 s0, v6
	s_mov_b32 m0, s0
	s_mov_b64 s[0:1], 0x66000
	v_add_u32_e32 v6, 0xe000, v152
	global_load_lds_dwordx4 v[4:5], off
	v_lshl_add_u64 v[4:5], v[18:19], 0, s[0:1]
	v_readfirstlane_b32 s0, v6
	s_mov_b32 m0, s0
	v_and_b32_e32 v147, 15, v20
	global_load_lds_dwordx4 v[4:5], off
	v_bfe_u32 v148, v20, 4, 2
	v_bfe_u32 v22, v20, 1, 3
	v_lshlrev_b32_e32 v23, 7, v147
	v_bitop3_b32 v24, v21, v22, 3 bitop3:0x6c
	v_bitop3_b32 v22, v148, v22, 4 bitop3:0x36
	v_bitop3_b32 v4, v21, 7, v20 bitop3:0x48
	v_lshl_or_b32 v150, v22, 4, v23
	v_ashrrev_i32_e32 v22, 1, v20
	v_lshlrev_b32_e32 v4, 4, v4
	v_bfe_u32 v146, v20, 7, 1
	v_and_b32_e32 v149, 0xffffff80, v22
	v_and_or_b32 v149, v20, 64, v149
	v_or_b32_e32 v16, v16, v4
	v_or_b32_e32 v12, v12, v4
	v_or_b32_e32 v8, v8, v4
	v_or_b32_e32 v2, v2, v4
	v_or_b32_e32 v0, v0, v4
	v_mov_b32_e32 v108, 0
	v_lshl_or_b32 v151, v24, 4, v23
	v_lshl_add_u64 v[128:129], s[62:63], 0, v[16:17]
	v_lshl_add_u64 v[130:131], s[64:65], 0, v[12:13]
	v_lshl_add_u64 v[132:133], s[64:65], 0, v[8:9]
	v_lshl_add_u64 v[134:135], s[64:65], 0, v[2:3]
	v_lshl_add_u64 v[144:145], s[64:65], 0, v[0:1]
	s_mov_b32 s0, 0
	s_mov_b64 s[8:9], 0
	v_mov_b32_e32 v109, v108
	v_mov_b32_e32 v110, v108
	v_mov_b32_e32 v111, v108
	v_mov_b32_e32 v0, v108
	v_mov_b32_e32 v1, v108
	v_mov_b32_e32 v2, v108
	v_mov_b32_e32 v3, v108
	v_mov_b32_e32 v4, v108
	v_mov_b32_e32 v5, v108
	v_mov_b32_e32 v6, v108
	v_mov_b32_e32 v7, v108
	v_mov_b32_e32 v8, v108
	v_mov_b32_e32 v9, v108
	v_mov_b32_e32 v10, v108
	v_mov_b32_e32 v11, v108
	v_mov_b32_e32 v16, v108
	v_mov_b32_e32 v17, v108
	v_mov_b32_e32 v18, v108
	v_mov_b32_e32 v19, v108
	v_mov_b32_e32 v24, v108
	v_mov_b32_e32 v25, v108
	v_mov_b32_e32 v26, v108
	v_mov_b32_e32 v27, v108
	v_mov_b32_e32 v32, v108
	v_mov_b32_e32 v33, v108
	v_mov_b32_e32 v34, v108
	v_mov_b32_e32 v35, v108
	v_mov_b32_e32 v40, v108
	v_mov_b32_e32 v41, v108
	v_mov_b32_e32 v42, v108
	v_mov_b32_e32 v43, v108
	v_mov_b32_e32 v12, v108
	v_mov_b32_e32 v13, v108
	v_mov_b32_e32 v14, v108
	v_mov_b32_e32 v15, v108
	v_mov_b32_e32 v20, v108
	v_mov_b32_e32 v21, v108
	v_mov_b32_e32 v22, v108
	v_mov_b32_e32 v23, v108
	v_mov_b32_e32 v28, v108
	v_mov_b32_e32 v29, v108
	v_mov_b32_e32 v30, v108
	v_mov_b32_e32 v31, v108
	v_mov_b32_e32 v36, v108
	v_mov_b32_e32 v37, v108
	v_mov_b32_e32 v38, v108
	v_mov_b32_e32 v39, v108
	v_mov_b32_e32 v48, v108
	v_mov_b32_e32 v49, v108
	v_mov_b32_e32 v50, v108
	v_mov_b32_e32 v51, v108
	v_mov_b32_e32 v56, v108
	v_mov_b32_e32 v57, v108
	v_mov_b32_e32 v58, v108
	v_mov_b32_e32 v59, v108
	v_mov_b32_e32 v64, v108
	v_mov_b32_e32 v65, v108
	v_mov_b32_e32 v66, v108
	v_mov_b32_e32 v67, v108
	v_mov_b32_e32 v72, v108
	v_mov_b32_e32 v73, v108
	v_mov_b32_e32 v74, v108
	v_mov_b32_e32 v75, v108
	v_mov_b32_e32 v44, v108
	v_mov_b32_e32 v45, v108
	v_mov_b32_e32 v46, v108
	v_mov_b32_e32 v47, v108
	v_mov_b32_e32 v52, v108
	v_mov_b32_e32 v53, v108
	v_mov_b32_e32 v54, v108
	v_mov_b32_e32 v55, v108
	v_mov_b32_e32 v60, v108
	v_mov_b32_e32 v61, v108
	v_mov_b32_e32 v62, v108
	v_mov_b32_e32 v63, v108
	v_mov_b32_e32 v68, v108
	v_mov_b32_e32 v69, v108
	v_mov_b32_e32 v70, v108
	v_mov_b32_e32 v71, v108
	v_mov_b32_e32 v80, v108
	v_mov_b32_e32 v81, v108
	v_mov_b32_e32 v82, v108
	v_mov_b32_e32 v83, v108
	v_mov_b32_e32 v88, v108
	v_mov_b32_e32 v89, v108
	v_mov_b32_e32 v90, v108
	v_mov_b32_e32 v91, v108
	v_mov_b32_e32 v96, v108
	v_mov_b32_e32 v97, v108
	v_mov_b32_e32 v98, v108
	v_mov_b32_e32 v99, v108
	v_mov_b32_e32 v104, v108
	v_mov_b32_e32 v105, v108
	v_mov_b32_e32 v106, v108
	v_mov_b32_e32 v107, v108
	v_mov_b32_e32 v76, v108
	v_mov_b32_e32 v77, v108
	v_mov_b32_e32 v78, v108
	v_mov_b32_e32 v79, v108
	v_mov_b32_e32 v84, v108
	v_mov_b32_e32 v85, v108
	v_mov_b32_e32 v86, v108
	v_mov_b32_e32 v87, v108
	v_mov_b32_e32 v92, v108
	v_mov_b32_e32 v93, v108
	v_mov_b32_e32 v94, v108
	v_mov_b32_e32 v95, v108
	v_mov_b32_e32 v100, v108
	v_mov_b32_e32 v101, v108
	v_mov_b32_e32 v102, v108
	v_mov_b32_e32 v103, v108
	v_mov_b32_e32 v112, v108
	v_mov_b32_e32 v113, v108
	v_mov_b32_e32 v114, v108
	v_mov_b32_e32 v115, v108
	v_mov_b32_e32 v116, v108
	v_mov_b32_e32 v117, v108
	v_mov_b32_e32 v118, v108
	v_mov_b32_e32 v119, v108
	v_mov_b32_e32 v120, v108
	v_mov_b32_e32 v121, v108
	v_mov_b32_e32 v122, v108
	v_mov_b32_e32 v123, v108
	v_mov_b32_e32 v124, v108
	v_mov_b32_e32 v125, v108
	v_mov_b32_e32 v126, v108
	v_mov_b32_e32 v127, v108
	v_lshlrev_b32_e32 v153, 7, v149
	v_lshlrev_b32_e32 v154, 14, v146
	v_readlane_b32 s98, v255, 2
	v_readlane_b32 s99, v255, 3
	v_readfirstlane_b32 s100, v152
	s_nop 3
	s_load_dwordx2 s[98:99], s[98:99], 0xf0
	s_waitcnt lgkmcnt(0)
	v_subrev_u32_e32 v251, s98, v144
	v_subrev_u32_e32 v250, s98, v134
	v_subrev_u32_e32 v249, s98, v132
	v_subrev_u32_e32 v248, s98, v130
	v_add_u32_e32 v247, s66, v128
	v_subrev_u32_e32 v247, s98, v247
	v_add_u32_e32 v246, 0x22080, v128
	v_subrev_u32_e32 v246, s98, v246
	v_add_u32_e32 v245, 0x44080, v128
	v_subrev_u32_e32 v245, s98, v245
	v_add_u32_e32 v244, 0x66080, v128
	v_subrev_u32_e32 v244, s98, v244
.LBB0_212:
	s_add_i32 s1, s0, 0x10000
	s_and_b32 s11, s1, 0x10000
	s_waitcnt vmcnt(0)
	s_barrier
	s_and_b32 s0, s0, 0x10000
	s_add_i32 s0, s0, 0
	v_add_u32_e32 v155, s0, v153
	v_add_u32_e32 v164, v155, v151
	ds_read_b128 v[156:159], v164
	ds_read_b128 v[160:163], v164 offset:2048
	ds_read_b128 v[178:181], v164 offset:4096
	ds_read_b128 v[182:185], v164 offset:6144
	v_add_u32_e32 v243, v155, v150
	v_add_u32_e32 v164, s0, v154
	v_add_u32_e32 v165, v164, v151
	ds_read_b128 v[186:189], v165 offset:32768
	ds_read_b128 v[192:195], v165 offset:34816
	ds_read_b128 v[198:201], v165 offset:36864
	ds_read_b128 v[204:207], v165 offset:38912
	v_add_u32_e32 v242, v164, v150
	s_add_i32 s101, s100, s11
	s_add_u32 s12, s98, s8
	s_addc_u32 s13, s99, s9
	s_mov_b32 m0, s101
	s_nop 0
	global_load_lds_dwordx4 v251, s[12:13]
	s_waitcnt lgkmcnt(0)
	v_mfma_f32_16x16x32_bf16 v[124:127], v[156:159], v[186:189], v[124:127]
	ds_read_b128 v[224:227], v165 offset:40960
	v_mfma_f32_16x16x32_bf16 v[120:123], v[156:159], v[192:195], v[120:123]
	ds_read_b128 v[228:231], v165 offset:43008
	v_mfma_f32_16x16x32_bf16 v[116:119], v[156:159], v[198:201], v[116:119]
	ds_read_b128 v[232:235], v165 offset:45056
	s_add_i32 m0, s101, 0x2000
	s_nop 0
	global_load_lds_dwordx4 v250, s[12:13]
	v_mfma_f32_16x16x32_bf16 v[112:115], v[156:159], v[204:207], v[112:115]
	ds_read_b128 v[236:239], v165 offset:47104
	v_mfma_f32_16x16x32_bf16 v[104:107], v[160:163], v[186:189], v[104:107]
	ds_read_b128 v[208:211], v243
	v_mfma_f32_16x16x32_bf16 v[96:99], v[160:163], v[192:195], v[96:99]
	ds_read_b128 v[212:215], v243 offset:2048
	s_add_i32 m0, s101, 0x4000
	s_nop 0
	global_load_lds_dwordx4 v249, s[12:13]
	v_mfma_f32_16x16x32_bf16 v[88:91], v[160:163], v[198:201], v[88:91]
	ds_read_b128 v[216:219], v243 offset:4096
	v_mfma_f32_16x16x32_bf16 v[80:83], v[160:163], v[204:207], v[80:83]
	ds_read_b128 v[220:223], v243 offset:6144
	v_mfma_f32_16x16x32_bf16 v[72:75], v[178:181], v[186:189], v[72:75]
	s_add_i32 m0, s101, 0x6000
	s_nop 0
	global_load_lds_dwordx4 v248, s[12:13]
	v_mfma_f32_16x16x32_bf16 v[64:67], v[178:181], v[192:195], v[64:67]
	v_mfma_f32_16x16x32_bf16 v[56:59], v[178:181], v[198:201], v[56:59]
	v_mfma_f32_16x16x32_bf16 v[48:51], v[178:181], v[204:207], v[48:51]
	s_add_i32 m0, s101, 0x8000
	s_nop 0
	global_load_lds_dwordx4 v247, s[12:13]
	v_mfma_f32_16x16x32_bf16 v[40:43], v[182:185], v[186:189], v[40:43]
	v_mfma_f32_16x16x32_bf16 v[32:35], v[182:185], v[192:195], v[32:35]
	v_mfma_f32_16x16x32_bf16 v[24:27], v[182:185], v[198:201], v[24:27]
	s_add_i32 m0, s101, 0xa000
	s_nop 0
	global_load_lds_dwordx4 v246, s[12:13]
	v_mfma_f32_16x16x32_bf16 v[16:19], v[182:185], v[204:207], v[16:19]
	s_waitcnt lgkmcnt(4)
	v_mfma_f32_16x16x32_bf16 v[100:103], v[156:159], v[224:227], v[100:103]
	v_mfma_f32_16x16x32_bf16 v[92:95], v[156:159], v[228:231], v[92:95]
	s_add_i32 m0, s101, 0xc000
	s_nop 0
	global_load_lds_dwordx4 v245, s[12:13]
	v_mfma_f32_16x16x32_bf16 v[84:87], v[156:159], v[232:235], v[84:87]
	ds_read_b128 v[186:189], v242 offset:32768
	v_mfma_f32_16x16x32_bf16 v[76:79], v[156:159], v[236:239], v[76:79]
	ds_read_b128 v[192:195], v242 offset:34816
	v_mfma_f32_16x16x32_bf16 v[68:71], v[160:163], v[224:227], v[68:71]
	ds_read_b128 v[198:201], v242 offset:36864
	s_add_i32 m0, s101, 0xe000
	s_nop 0
	global_load_lds_dwordx4 v244, s[12:13]
	v_mfma_f32_16x16x32_bf16 v[60:63], v[160:163], v[228:231], v[60:63]
	ds_read_b128 v[204:207], v242 offset:38912
	v_mfma_f32_16x16x32_bf16 v[52:55], v[160:163], v[232:235], v[52:55]
	v_mfma_f32_16x16x32_bf16 v[44:47], v[160:163], v[236:239], v[44:47]
	v_mfma_f32_16x16x32_bf16 v[36:39], v[178:181], v[224:227], v[36:39]
	v_mfma_f32_16x16x32_bf16 v[28:31], v[178:181], v[228:231], v[28:31]
	v_mfma_f32_16x16x32_bf16 v[20:23], v[178:181], v[232:235], v[20:23]
	v_mfma_f32_16x16x32_bf16 v[12:15], v[178:181], v[236:239], v[12:15]
	v_mfma_f32_16x16x32_bf16 v[8:11], v[182:185], v[224:227], v[8:11]
	v_mfma_f32_16x16x32_bf16 v[4:7], v[182:185], v[228:231], v[4:7]
	v_mfma_f32_16x16x32_bf16 v[0:3], v[182:185], v[232:235], v[0:3]
	v_mfma_f32_16x16x32_bf16 v[108:111], v[182:185], v[236:239], v[108:111]
	s_waitcnt lgkmcnt(0)
	v_mfma_f32_16x16x32_bf16 v[124:127], v[208:211], v[186:189], v[124:127]
	ds_read_b128 v[224:227], v242 offset:40960
	v_mfma_f32_16x16x32_bf16 v[120:123], v[208:211], v[192:195], v[120:123]
	ds_read_b128 v[228:231], v242 offset:43008
	v_mfma_f32_16x16x32_bf16 v[116:119], v[208:211], v[198:201], v[116:119]
	ds_read_b128 v[232:235], v242 offset:45056
	v_mfma_f32_16x16x32_bf16 v[112:115], v[208:211], v[204:207], v[112:115]
	ds_read_b128 v[236:239], v242 offset:47104
	v_mfma_f32_16x16x32_bf16 v[104:107], v[212:215], v[186:189], v[104:107]
	v_mfma_f32_16x16x32_bf16 v[96:99], v[212:215], v[192:195], v[96:99]
	v_mfma_f32_16x16x32_bf16 v[88:91], v[212:215], v[198:201], v[88:91]
	v_mfma_f32_16x16x32_bf16 v[80:83], v[212:215], v[204:207], v[80:83]
	v_mfma_f32_16x16x32_bf16 v[72:75], v[216:219], v[186:189], v[72:75]
	v_mfma_f32_16x16x32_bf16 v[64:67], v[216:219], v[192:195], v[64:67]
	v_mfma_f32_16x16x32_bf16 v[56:59], v[216:219], v[198:201], v[56:59]
	v_mfma_f32_16x16x32_bf16 v[48:51], v[216:219], v[204:207], v[48:51]
	v_mfma_f32_16x16x32_bf16 v[40:43], v[220:223], v[186:189], v[40:43]
	v_mfma_f32_16x16x32_bf16 v[32:35], v[220:223], v[192:195], v[32:35]
	v_mfma_f32_16x16x32_bf16 v[24:27], v[220:223], v[198:201], v[24:27]
	v_mfma_f32_16x16x32_bf16 v[16:19], v[220:223], v[204:207], v[16:19]
	s_waitcnt lgkmcnt(0)
	v_mfma_f32_16x16x32_bf16 v[100:103], v[208:211], v[224:227], v[100:103]
	v_mfma_f32_16x16x32_bf16 v[92:95], v[208:211], v[228:231], v[92:95]
	v_mfma_f32_16x16x32_bf16 v[84:87], v[208:211], v[232:235], v[84:87]
	v_mfma_f32_16x16x32_bf16 v[76:79], v[208:211], v[236:239], v[76:79]
	v_mfma_f32_16x16x32_bf16 v[68:71], v[212:215], v[224:227], v[68:71]
	v_mfma_f32_16x16x32_bf16 v[60:63], v[212:215], v[228:231], v[60:63]
	v_mfma_f32_16x16x32_bf16 v[52:55], v[212:215], v[232:235], v[52:55]
	v_mfma_f32_16x16x32_bf16 v[44:47], v[212:215], v[236:239], v[44:47]
	v_mfma_f32_16x16x32_bf16 v[36:39], v[216:219], v[224:227], v[36:39]
	v_mfma_f32_16x16x32_bf16 v[28:31], v[216:219], v[228:231], v[28:31]
	v_mfma_f32_16x16x32_bf16 v[20:23], v[216:219], v[232:235], v[20:23]
	v_mfma_f32_16x16x32_bf16 v[12:15], v[216:219], v[236:239], v[12:15]
	s_add_u32 s8, s8, 0x80
	s_addc_u32 s9, s9, 0
	s_cmpk_eq_i32 s8, 0x780
	s_mov_b32 s0, s1
	v_mfma_f32_16x16x32_bf16 v[8:11], v[220:223], v[224:227], v[8:11]
	v_mfma_f32_16x16x32_bf16 v[4:7], v[220:223], v[228:231], v[4:7]
	v_mfma_f32_16x16x32_bf16 v[0:3], v[220:223], v[232:235], v[0:3]
	v_mfma_f32_16x16x32_bf16 v[108:111], v[220:223], v[236:239], v[108:111]
	s_cbranch_scc0 .LBB0_212
	s_add_i32 s0, 0, 0x10000
	v_add_u32_e32 v144, s0, v154
	v_add_u32_e32 v162, s0, v153
	v_add_u32_e32 v145, v144, v151
	v_add_u32_e32 v151, v162, v151
	s_waitcnt vmcnt(0)
	s_barrier
	ds_read_b128 v[128:131], v145 offset:38912
	ds_read_b128 v[132:135], v145 offset:36864
	ds_read_b128 v[154:157], v145 offset:34816
	ds_read_b128 v[158:161], v145 offset:32768
	ds_read_b128 v[178:181], v151 offset:6144
	ds_read_b128 v[182:185], v151 offset:4096
	ds_read_b128 v[186:189], v151 offset:2048
	ds_read_b128 v[204:207], v151
	s_waitcnt lgkmcnt(0)
	v_mfma_f32_16x16x32_bf16 v[124:127], v[204:207], v[158:161], v[124:127]
	v_mfma_f32_16x16x32_bf16 v[120:123], v[204:207], v[154:157], v[120:123]
	v_mfma_f32_16x16x32_bf16 v[116:119], v[204:207], v[132:135], v[116:119]
	v_mfma_f32_16x16x32_bf16 v[112:115], v[204:207], v[128:131], v[112:115]
	v_mfma_f32_16x16x32_bf16 v[104:107], v[186:189], v[158:161], v[104:107]
	v_mfma_f32_16x16x32_bf16 v[72:75], v[182:185], v[158:161], v[72:75]
	v_mfma_f32_16x16x32_bf16 v[64:67], v[182:185], v[154:157], v[64:67]
	v_mfma_f32_16x16x32_bf16 v[56:59], v[182:185], v[132:135], v[56:59]
	v_mfma_f32_16x16x32_bf16 v[48:51], v[182:185], v[128:131], v[48:51]
	v_mfma_f32_16x16x32_bf16 v[208:211], v[186:189], v[154:157], v[96:99]
	v_mfma_f32_16x16x32_bf16 v[212:215], v[186:189], v[132:135], v[88:91]
	v_mfma_f32_16x16x32_bf16 v[216:219], v[186:189], v[128:131], v[80:83]
	v_mfma_f32_16x16x32_bf16 v[158:161], v[178:181], v[158:161], v[40:43]
	v_mfma_f32_16x16x32_bf16 v[152:155], v[178:181], v[154:157], v[32:35]
	v_mfma_f32_16x16x32_bf16 v[132:135], v[178:181], v[132:135], v[24:27]
	v_mfma_f32_16x16x32_bf16 v[128:131], v[178:181], v[128:131], v[16:19]
	s_nop 2
	ds_read_b128 v[16:19], v145 offset:40960
	ds_read_b128 v[24:27], v145 offset:43008
	ds_read_b128 v[32:35], v145 offset:45056
	ds_read_b128 v[40:43], v145 offset:47104
	s_waitcnt lgkmcnt(0)
	v_mfma_f32_16x16x32_bf16 v[100:103], v[204:207], v[16:19], v[100:103]
	v_mfma_f32_16x16x32_bf16 v[92:95], v[204:207], v[24:27], v[92:95]
	v_mfma_f32_16x16x32_bf16 v[220:223], v[204:207], v[32:35], v[84:87]
	v_mfma_f32_16x16x32_bf16 v[76:79], v[204:207], v[40:43], v[76:79]
	v_mfma_f32_16x16x32_bf16 v[68:71], v[186:189], v[16:19], v[68:71]
	v_mfma_f32_16x16x32_bf16 v[60:63], v[186:189], v[24:27], v[60:63]
	v_mfma_f32_16x16x32_bf16 v[204:207], v[186:189], v[32:35], v[52:55]
	v_mfma_f32_16x16x32_bf16 v[44:47], v[186:189], v[40:43], v[44:47]
	v_mfma_f32_16x16x32_bf16 v[186:189], v[182:185], v[16:19], v[36:39]
	v_mfma_f32_16x16x32_bf16 v[224:227], v[182:185], v[24:27], v[28:31]
	v_mfma_f32_16x16x32_bf16 v[228:231], v[182:185], v[32:35], v[20:23]
	v_mfma_f32_16x16x32_bf16 v[182:185], v[182:185], v[40:43], v[12:15]
	v_mfma_f32_16x16x32_bf16 v[232:235], v[178:181], v[16:19], v[8:11]
	v_mfma_f32_16x16x32_bf16 v[236:239], v[178:181], v[24:27], v[4:7]
	v_mfma_f32_16x16x32_bf16 v[240:243], v[178:181], v[32:35], v[0:3]
	v_mfma_f32_16x16x32_bf16 v[244:247], v[178:181], v[40:43], v[108:111]
	s_nop 1
	v_add_u32_e32 v0, v162, v150
	v_add_u32_e32 v144, v144, v150
	ds_read_b128 v[108:111], v0
	ds_read_b128 v[178:181], v0 offset:2048
	ds_read_b128 v[248:251], v0 offset:4096
	ds_read_b128 v[192:195], v0 offset:6144
	ds_read_b128 v[0:3], v144 offset:32768
	ds_read_b128 v[4:7], v144 offset:34816
	ds_read_b128 v[198:201], v144 offset:36864
	ds_read_b128 v[162:165], v144 offset:38912
	s_waitcnt lgkmcnt(0)
	v_mfma_f32_16x16x32_bf16 v[88:91], v[108:111], v[0:3], v[124:127]
	v_mfma_f32_16x16x32_bf16 v[96:99], v[108:111], v[4:7], v[120:123]
	v_mfma_f32_16x16x32_bf16 v[80:83], v[108:111], v[198:201], v[116:119]
	v_mfma_f32_16x16x32_bf16 v[84:87], v[108:111], v[162:165], v[112:115]
	v_mfma_f32_16x16x32_bf16 v[40:43], v[178:181], v[0:3], v[104:107]
	v_mfma_f32_16x16x32_bf16 v[52:55], v[178:181], v[4:7], v[208:211]
	v_mfma_f32_16x16x32_bf16 v[32:35], v[178:181], v[198:201], v[212:215]
	v_mfma_f32_16x16x32_bf16 v[36:39], v[178:181], v[162:165], v[216:219]
	v_mfma_f32_16x16x32_bf16 v[24:27], v[248:251], v[0:3], v[72:75]
	v_mfma_f32_16x16x32_bf16 v[28:31], v[248:251], v[4:7], v[64:67]
	v_mfma_f32_16x16x32_bf16 v[16:19], v[248:251], v[198:201], v[56:59]
	v_mfma_f32_16x16x32_bf16 v[20:23], v[248:251], v[162:165], v[48:51]
	v_mfma_f32_16x16x32_bf16 v[8:11], v[192:195], v[0:3], v[158:161]
	v_mfma_f32_16x16x32_bf16 v[12:15], v[192:195], v[4:7], v[152:155]
	v_mfma_f32_16x16x32_bf16 v[0:3], v[192:195], v[198:201], v[132:135]
	v_mfma_f32_16x16x32_bf16 v[4:7], v[192:195], v[162:165], v[128:131]
	ds_read_b128 v[48:51], v144 offset:40960
	ds_read_b128 v[64:67], v144 offset:43008
	s_nop 0
	ds_read_b128 v[128:131], v144 offset:45056
	ds_read_b128 v[132:135], v144 offset:47104
	s_waitcnt lgkmcnt(0)
	v_mfma_f32_16x16x32_bf16 v[104:107], v[178:181], v[48:51], v[68:71]
	v_cmp_ne_u32_e64 s[8:9], 0, v146
	v_cmp_eq_u32_e32 vcc, 0, v146
	s_waitcnt vmcnt(0)
	v_lshl_or_b32 v68, v148, 2, v149
	v_lshl_add_u32 v69, v147, 2, 0
	v_mfma_f32_16x16x32_bf16 v[120:123], v[108:111], v[48:51], v[100:103]
	s_barrier
	v_mfma_f32_16x16x32_bf16 v[124:127], v[108:111], v[64:67], v[92:95]
	v_mfma_f32_16x16x32_bf16 v[112:115], v[108:111], v[128:131], v[220:223]
	v_mfma_f32_16x16x32_bf16 v[116:119], v[108:111], v[132:135], v[76:79]
	v_mfma_f32_16x16x32_bf16 v[108:111], v[178:181], v[64:67], v[60:63]
	v_mfma_f32_16x16x32_bf16 v[92:95], v[178:181], v[128:131], v[204:207]
	v_mfma_f32_16x16x32_bf16 v[100:103], v[178:181], v[132:135], v[44:47]
	v_mfma_f32_16x16x32_bf16 v[56:59], v[248:251], v[48:51], v[186:189]
	v_mfma_f32_16x16x32_bf16 v[60:63], v[248:251], v[64:67], v[224:227]
	v_mfma_f32_16x16x32_bf16 v[44:47], v[248:251], v[128:131], v[228:231]
	v_mfma_f32_16x16x32_bf16 v[72:75], v[248:251], v[132:135], v[182:185]
	v_mfma_f32_16x16x32_bf16 v[48:51], v[192:195], v[48:51], v[232:235]
	s_nop 1
	v_lshl_add_u32 v182, v68, 9, v69
	v_add_u32_e32 v183, 0x400, v182
	v_add_u32_e32 v181, 0x2000, v182
	v_mfma_f32_16x16x32_bf16 v[64:67], v[192:195], v[64:67], v[236:239]
	v_add_u32_e32 v180, 0x2400, v182
	v_add_u32_e32 v179, 0x4000, v182
	v_add_u32_e32 v178, 0x4400, v182
	v_mfma_f32_16x16x32_bf16 v[68:71], v[192:195], v[128:131], v[240:243]
	v_add_u32_e32 v175, 0x6000, v182
	v_add_u32_e32 v174, 0x6400, v182
	v_mfma_f32_16x16x32_bf16 v[76:79], v[192:195], v[132:135], v[244:247]
	s_and_saveexec_b64 s[0:1], vcc
	s_cbranch_execz .LBB0_215
	ds_write2_b32 v182, v88, v96 offset1:16
	ds_write2_b32 v182, v89, v97 offset0:128 offset1:144
	ds_write2_b32 v183, v90, v98 offset1:16
	ds_write2_b32 v183, v91, v99 offset0:128 offset1:144
	ds_write2_b32 v182, v80, v84 offset0:32 offset1:48
	ds_write2_b32 v182, v81, v85 offset0:160 offset1:176
	ds_write2_b32 v183, v82, v86 offset0:32 offset1:48
	ds_write2_b32 v183, v83, v87 offset0:160 offset1:176
	ds_write2_b32 v182, v120, v124 offset0:64 offset1:80
	ds_write2_b32 v182, v121, v125 offset0:192 offset1:208
	ds_write2_b32 v183, v122, v126 offset0:64 offset1:80
	ds_write2_b32 v183, v123, v127 offset0:192 offset1:208
	ds_write2_b32 v182, v112, v116 offset0:96 offset1:112
	ds_write2_b32 v182, v113, v117 offset0:224 offset1:240
	ds_write2_b32 v183, v114, v118 offset0:96 offset1:112
	ds_write2_b32 v183, v115, v119 offset0:224 offset1:240
	ds_write2_b32 v181, v40, v52 offset1:16
	ds_write2_b32 v181, v41, v53 offset0:128 offset1:144
	ds_write2_b32 v180, v42, v54 offset1:16
	ds_write2_b32 v180, v43, v55 offset0:128 offset1:144
	ds_write2_b32 v181, v32, v36 offset0:32 offset1:48
	ds_write2_b32 v181, v33, v37 offset0:160 offset1:176
	ds_write2_b32 v180, v34, v38 offset0:32 offset1:48
	ds_write2_b32 v180, v35, v39 offset0:160 offset1:176
	ds_write2_b32 v181, v104, v108 offset0:64 offset1:80
	ds_write2_b32 v181, v105, v109 offset0:192 offset1:208
	ds_write2_b32 v180, v106, v110 offset0:64 offset1:80
	ds_write2_b32 v180, v107, v111 offset0:192 offset1:208
	ds_write2_b32 v181, v92, v100 offset0:96 offset1:112
	ds_write2_b32 v181, v93, v101 offset0:224 offset1:240
	ds_write2_b32 v180, v94, v102 offset0:96 offset1:112
	ds_write2_b32 v180, v95, v103 offset0:224 offset1:240
	ds_write2_b32 v179, v24, v28 offset1:16
	ds_write2_b32 v179, v25, v29 offset0:128 offset1:144
	ds_write2_b32 v178, v26, v30 offset1:16
	ds_write2_b32 v178, v27, v31 offset0:128 offset1:144
	ds_write2_b32 v179, v16, v20 offset0:32 offset1:48
	ds_write2_b32 v179, v17, v21 offset0:160 offset1:176
	ds_write2_b32 v178, v18, v22 offset0:32 offset1:48
	ds_write2_b32 v178, v19, v23 offset0:160 offset1:176
	ds_write2_b32 v179, v56, v60 offset0:64 offset1:80
	ds_write2_b32 v179, v57, v61 offset0:192 offset1:208
	ds_write2_b32 v178, v58, v62 offset0:64 offset1:80
	ds_write2_b32 v178, v59, v63 offset0:192 offset1:208
	ds_write2_b32 v179, v44, v72 offset0:96 offset1:112
	ds_write2_b32 v179, v45, v73 offset0:224 offset1:240
	ds_write2_b32 v178, v46, v74 offset0:96 offset1:112
	ds_write2_b32 v178, v47, v75 offset0:224 offset1:240
	ds_write2_b32 v175, v8, v12 offset1:16
	ds_write2_b32 v175, v9, v13 offset0:128 offset1:144
	ds_write2_b32 v174, v10, v14 offset1:16
	ds_write2_b32 v174, v11, v15 offset0:128 offset1:144
	ds_write2_b32 v175, v0, v4 offset0:32 offset1:48
	ds_write2_b32 v175, v1, v5 offset0:160 offset1:176
	ds_write2_b32 v174, v2, v6 offset0:32 offset1:48
	ds_write2_b32 v174, v3, v7 offset0:160 offset1:176
	ds_write2_b32 v175, v48, v64 offset0:64 offset1:80
	ds_write2_b32 v175, v49, v65 offset0:192 offset1:208
	ds_write2_b32 v174, v50, v66 offset0:64 offset1:80
	ds_write2_b32 v174, v51, v67 offset0:192 offset1:208
	ds_write2_b32 v175, v68, v76 offset0:96 offset1:112
	ds_write2_b32 v175, v69, v77 offset0:224 offset1:240
	ds_write2_b32 v174, v70, v78 offset0:96 offset1:112
	ds_write2_b32 v174, v71, v79 offset0:224 offset1:240

.LBB0_658:
	s_ashr_i32 s2, s0, 7
	s_mul_i32 s1, s2, 33
	s_bfe_u32 s3, s0, 0x50002
	s_add_i32 s10, s1, s3
	s_add_i32 s10, s10, 1
	v_mov_b32_e32 v14, v190
	s_lshl_b32 s17, s10, 8
	s_lshl_b32 s0, s0, 8
	s_and_b32 s12, s0, 0x300
	v_ashrrev_i32_e32 v15, 3, v14
	v_lshrrev_b32_e32 v16, 4, v14
	v_add_u32_e32 v18, s17, v15
	v_xor_b32_e32 v17, v16, v14
	v_add_u32_e32 v2, 64, v18
	v_mov_b64_e32 v[0:1], s[42:43]
	v_add_u32_e32 v4, 0x80, v18
	v_add_u32_e32 v6, 0xc0, v18
	v_add_u32_e32 v12, s12, v15
	v_mov_b64_e32 v[10:11], s[58:59]
	v_mad_i64_i32 v[2:3], s[0:1], v2, s78, v[0:1]
	v_mad_i64_i32 v[4:5], s[0:1], v4, s78, v[0:1]
	v_mad_i64_i32 v[6:7], s[0:1], v6, s78, v[0:1]
	v_mad_i64_i32 v[8:9], s[0:1], v12, s78, 0
	v_mad_i64_i32 v[10:11], s[0:1], v12, s78, v[10:11]
	v_mad_i64_i32 v[12:13], s[0:1], v18, s78, 0
	v_mad_i64_i32 v[0:1], s[0:1], v18, s78, v[0:1]
	v_lshlrev_b32_e32 v17, 4, v17
	v_lshl_add_u32 v150, v14, 4, 0
	v_and_b32_e32 v176, 0x70, v17
	v_readfirstlane_b32 s0, v150
	v_lshl_add_u64 v[0:1], v[0:1], 0, v[176:177]
	s_mov_b32 m0, s0
	v_lshl_add_u64 v[2:3], v[2:3], 0, v[176:177]
	global_load_lds_dwordx4 v[0:1], off
	v_add_u32_e32 v0, 0x2000, v150
	v_lshl_add_u64 v[4:5], v[4:5], 0, v[176:177]
	v_readfirstlane_b32 s0, v0
	v_add_u32_e32 v0, 0x4000, v150
	s_mov_b32 m0, s0
	v_readfirstlane_b32 s0, v0
	v_add_u32_e32 v0, 0x6000, v150
	global_load_lds_dwordx4 v[2:3], off
	s_mov_b32 m0, s0
	v_readfirstlane_b32 s0, v0
	v_add_u32_e32 v0, 0x8000, v150
	v_lshl_add_u64 v[6:7], v[6:7], 0, v[176:177]
	global_load_lds_dwordx4 v[4:5], off
	s_mov_b32 m0, s0
	v_readfirstlane_b32 s0, v0
	v_lshl_add_u64 v[10:11], v[10:11], 0, v[176:177]
	global_load_lds_dwordx4 v[6:7], off
	s_mov_b32 m0, s0
	s_mov_b64 s[0:1], 0x22000
	v_add_u32_e32 v2, 0xa000, v150
	v_lshl_add_u64 v[0:1], v[10:11], 0, s[0:1]
	v_readfirstlane_b32 s0, v2
	global_load_lds_dwordx4 v[10:11], off
	s_mov_b32 m0, s0
	s_mov_b64 s[0:1], 0x44000
	v_add_u32_e32 v2, 0xc000, v150
	global_load_lds_dwordx4 v[0:1], off
	v_lshl_add_u64 v[0:1], v[10:11], 0, s[0:1]
	v_readfirstlane_b32 s0, v2
	s_mov_b32 m0, s0
	s_mov_b64 s[0:1], 0x66000
	v_add_u32_e32 v2, 0xe000, v150
	global_load_lds_dwordx4 v[0:1], off
	v_lshl_add_u64 v[0:1], v[10:11], 0, s[0:1]
	v_readfirstlane_b32 s0, v2
	s_mov_b32 m0, s0
	s_mulk_i32 s2, 0x2100
	global_load_lds_dwordx4 v[0:1], off
	s_lshl_b32 s13, s3, 8
	s_add_i32 s13, s13, s2
	v_bitop3_b32 v0, v16, 7, v14 bitop3:0x48
	v_add_u32_e32 v3, s13, v15
	v_lshlrev_b32_e32 v2, 4, v0
	v_add_u32_e32 v0, 0x140, v3
	v_mad_i64_i32 v[0:1], s[0:1], v0, s78, 0
	v_or_b32_e32 v0, v0, v2
	v_lshl_add_u64 v[130:131], s[48:49], 0, v[0:1]
	v_add_u32_e32 v0, 0x180, v3
	v_mad_i64_i32 v[0:1], s[0:1], v0, s78, 0
	v_and_b32_e32 v139, 15, v14
	v_bfe_u32 v140, v14, 4, 2
	v_bfe_u32 v17, v14, 1, 3
	v_or_b32_e32 v0, v0, v2
	v_lshlrev_b32_e32 v18, 7, v139
	v_bitop3_b32 v19, v16, v17, 3 bitop3:0x6c
	v_bitop3_b32 v17, v140, v17, 4 bitop3:0x36
	v_lshl_add_u64 v[132:133], s[48:49], 0, v[0:1]
	v_add_u32_e32 v0, 0x1c0, v3
	v_lshl_or_b32 v146, v17, 4, v18
	v_ashrrev_i32_e32 v17, 1, v14
	v_mad_i64_i32 v[0:1], s[0:1], v0, s78, 0
	v_bfe_u32 v138, v14, 7, 1
	v_and_b32_e32 v141, 0xffffff80, v17
	v_and_or_b32 v141, v14, 64, v141
	v_or_b32_e32 v12, v12, v2
	v_or_b32_e32 v0, v0, v2
	v_or_b32_e32 v8, v8, v2
	v_mov_b32_e32 v108, 0
	v_lshl_or_b32 v147, v19, 4, v18
	v_lshlrev_b32_e32 v149, 7, v141
	v_lshlrev_b32_e32 v148, 14, v138
	v_lshl_add_u64 v[128:129], s[48:49], 0, v[12:13]
	v_lshl_add_u64 v[134:135], s[48:49], 0, v[0:1]
	v_lshl_add_u64 v[136:137], s[8:9], 0, v[8:9]
	s_mov_b64 s[2:3], 0
	s_mov_b32 s0, 0
	v_mov_b32_e32 v109, v108
	v_mov_b32_e32 v110, v108
	v_mov_b32_e32 v111, v108
	v_mov_b32_e32 v0, v108
	v_mov_b32_e32 v1, v108
	v_mov_b32_e32 v2, v108
	v_mov_b32_e32 v3, v108
	v_mov_b32_e32 v4, v108
	v_mov_b32_e32 v5, v108
	v_mov_b32_e32 v6, v108
	v_mov_b32_e32 v7, v108
	v_mov_b32_e32 v8, v108
	v_mov_b32_e32 v9, v108
	v_mov_b32_e32 v10, v108
	v_mov_b32_e32 v11, v108
	v_mov_b32_e32 v16, v108
	v_mov_b32_e32 v17, v108
	v_mov_b32_e32 v18, v108
	v_mov_b32_e32 v19, v108
	v_mov_b32_e32 v24, v108
	v_mov_b32_e32 v25, v108
	v_mov_b32_e32 v26, v108
	v_mov_b32_e32 v27, v108
	v_mov_b32_e32 v32, v108
	v_mov_b32_e32 v33, v108
	v_mov_b32_e32 v34, v108
	v_mov_b32_e32 v35, v108
	v_mov_b32_e32 v40, v108
	v_mov_b32_e32 v41, v108
	v_mov_b32_e32 v42, v108
	v_mov_b32_e32 v43, v108
	v_mov_b32_e32 v12, v108
	v_mov_b32_e32 v13, v108
	v_mov_b32_e32 v14, v108
	v_mov_b32_e32 v15, v108
	v_mov_b32_e32 v20, v108
	v_mov_b32_e32 v21, v108
	v_mov_b32_e32 v22, v108
	v_mov_b32_e32 v23, v108
	v_mov_b32_e32 v28, v108
	v_mov_b32_e32 v29, v108
	v_mov_b32_e32 v30, v108
	v_mov_b32_e32 v31, v108
	v_mov_b32_e32 v36, v108
	v_mov_b32_e32 v37, v108
	v_mov_b32_e32 v38, v108
	v_mov_b32_e32 v39, v108
	v_mov_b32_e32 v48, v108
	v_mov_b32_e32 v49, v108
	v_mov_b32_e32 v50, v108
	v_mov_b32_e32 v51, v108
	v_mov_b32_e32 v56, v108
	v_mov_b32_e32 v57, v108
	v_mov_b32_e32 v58, v108
	v_mov_b32_e32 v59, v108
	v_mov_b32_e32 v64, v108
	v_mov_b32_e32 v65, v108
	v_mov_b32_e32 v66, v108
	v_mov_b32_e32 v67, v108
	v_mov_b32_e32 v72, v108
	v_mov_b32_e32 v73, v108
	v_mov_b32_e32 v74, v108
	v_mov_b32_e32 v75, v108
	v_mov_b32_e32 v44, v108
	v_mov_b32_e32 v45, v108
	v_mov_b32_e32 v46, v108
	v_mov_b32_e32 v47, v108
	v_mov_b32_e32 v52, v108
	v_mov_b32_e32 v53, v108
	v_mov_b32_e32 v54, v108
	v_mov_b32_e32 v55, v108
	v_mov_b32_e32 v60, v108
	v_mov_b32_e32 v61, v108
	v_mov_b32_e32 v62, v108
	v_mov_b32_e32 v63, v108
	v_mov_b32_e32 v68, v108
	v_mov_b32_e32 v69, v108
	v_mov_b32_e32 v70, v108
	v_mov_b32_e32 v71, v108
	v_mov_b32_e32 v80, v108
	v_mov_b32_e32 v81, v108
	v_mov_b32_e32 v82, v108
	v_mov_b32_e32 v83, v108
	v_mov_b32_e32 v88, v108
	v_mov_b32_e32 v89, v108
	v_mov_b32_e32 v90, v108
	v_mov_b32_e32 v91, v108
	v_mov_b32_e32 v96, v108
	v_mov_b32_e32 v97, v108
	v_mov_b32_e32 v98, v108
	v_mov_b32_e32 v99, v108
	v_mov_b32_e32 v104, v108
	v_mov_b32_e32 v105, v108
	v_mov_b32_e32 v106, v108
	v_mov_b32_e32 v107, v108
	v_mov_b32_e32 v76, v108
	v_mov_b32_e32 v77, v108
	v_mov_b32_e32 v78, v108
	v_mov_b32_e32 v79, v108
	v_mov_b32_e32 v84, v108
	v_mov_b32_e32 v85, v108
	v_mov_b32_e32 v86, v108
	v_mov_b32_e32 v87, v108
	v_mov_b32_e32 v92, v108
	v_mov_b32_e32 v93, v108
	v_mov_b32_e32 v94, v108
	v_mov_b32_e32 v95, v108
	v_mov_b32_e32 v100, v108
	v_mov_b32_e32 v101, v108
	v_mov_b32_e32 v102, v108
	v_mov_b32_e32 v103, v108
	v_mov_b32_e32 v112, v108
	v_mov_b32_e32 v113, v108
	v_mov_b32_e32 v114, v108
	v_mov_b32_e32 v115, v108
	v_mov_b32_e32 v116, v108
	v_mov_b32_e32 v117, v108
	v_mov_b32_e32 v118, v108
	v_mov_b32_e32 v119, v108
	v_mov_b32_e32 v120, v108
	v_mov_b32_e32 v121, v108
	v_mov_b32_e32 v122, v108
	v_mov_b32_e32 v123, v108
	v_mov_b32_e32 v124, v108
	v_mov_b32_e32 v125, v108
	v_mov_b32_e32 v126, v108
	v_mov_b32_e32 v127, v108
	v_readlane_b32 s98, v255, 2
	v_readlane_b32 s99, v255, 3
	v_readfirstlane_b32 s100, v150
	s_nop 3
	s_load_dwordx2 s[98:99], s[98:99], 0xf0
	s_waitcnt lgkmcnt(0)
	v_subrev_u32_e32 v254, s98, v128
	v_subrev_u32_e32 v253, s98, v130
	v_subrev_u32_e32 v251, s98, v132
	v_subrev_u32_e32 v250, s98, v134
	v_add_u32_e32 v249, 0x550080, v136
	v_subrev_u32_e32 v249, s98, v249
	v_add_u32_e32 v248, 0x572080, v136
	v_subrev_u32_e32 v248, s98, v248
	v_add_u32_e32 v243, 0x594080, v136
	v_subrev_u32_e32 v243, s98, v243
	v_add_u32_e32 v242, 0x5b6080, v136
	v_subrev_u32_e32 v242, s98, v242
.LBB0_659:
	s_add_i32 s1, s0, 0x10000
	s_and_b32 s11, s1, 0x10000
	s_waitcnt vmcnt(0)
	s_barrier
	s_and_b32 s0, s0, 0x10000
	s_add_i32 s0, s0, 0
	v_add_u32_e32 v151, s0, v149
	v_add_u32_e32 v164, v151, v147
	ds_read_b128 v[152:155], v164
	ds_read_b128 v[156:159], v164 offset:2048
	ds_read_b128 v[160:163], v164 offset:4096
	ds_read_b128 v[164:167], v164 offset:6144
	v_add_u32_e32 v241, v151, v146
	v_add_u32_e32 v176, s0, v148
	v_add_u32_e32 v186, v176, v147
	ds_read_b128 v[168:171], v186 offset:32768
	ds_read_b128 v[172:175], v186 offset:34816
	ds_read_b128 v[178:181], v186 offset:36864
	ds_read_b128 v[182:185], v186 offset:38912
	v_add_u32_e32 v240, v176, v146
	s_add_i32 s101, s100, s11
	s_add_u32 s18, s98, s2
	s_addc_u32 s19, s99, s3
	s_mov_b32 m0, s101
	s_nop 0
	global_load_lds_dwordx4 v254, s[18:19]
	s_waitcnt lgkmcnt(0)
	v_mfma_f32_16x16x32_bf16 v[124:127], v[152:155], v[168:171], v[124:127]
	ds_read_b128 v[212:215], v186 offset:40960
	v_mfma_f32_16x16x32_bf16 v[120:123], v[152:155], v[172:175], v[120:123]
	ds_read_b128 v[216:219], v186 offset:43008
	v_mfma_f32_16x16x32_bf16 v[116:119], v[152:155], v[178:181], v[116:119]
	ds_read_b128 v[220:223], v186 offset:45056
	s_add_i32 m0, s101, 0x2000
	s_nop 0
	global_load_lds_dwordx4 v253, s[18:19]
	v_mfma_f32_16x16x32_bf16 v[112:115], v[152:155], v[182:185], v[112:115]
	ds_read_b128 v[224:227], v186 offset:47104
	v_mfma_f32_16x16x32_bf16 v[104:107], v[156:159], v[168:171], v[104:107]
	ds_read_b128 v[192:195], v241
	v_mfma_f32_16x16x32_bf16 v[96:99], v[156:159], v[172:175], v[96:99]
	ds_read_b128 v[198:201], v241 offset:2048
	s_add_i32 m0, s101, 0x4000
	s_nop 0
	global_load_lds_dwordx4 v251, s[18:19]
	v_mfma_f32_16x16x32_bf16 v[88:91], v[156:159], v[178:181], v[88:91]
	ds_read_b128 v[204:207], v241 offset:4096
	v_mfma_f32_16x16x32_bf16 v[80:83], v[156:159], v[182:185], v[80:83]
	ds_read_b128 v[208:211], v241 offset:6144
	v_mfma_f32_16x16x32_bf16 v[72:75], v[160:163], v[168:171], v[72:75]
	s_add_i32 m0, s101, 0x6000
	s_nop 0
	global_load_lds_dwordx4 v250, s[18:19]
	v_mfma_f32_16x16x32_bf16 v[64:67], v[160:163], v[172:175], v[64:67]
	v_mfma_f32_16x16x32_bf16 v[56:59], v[160:163], v[178:181], v[56:59]
	v_mfma_f32_16x16x32_bf16 v[48:51], v[160:163], v[182:185], v[48:51]
	s_add_i32 m0, s101, 0x8000
	s_nop 0
	global_load_lds_dwordx4 v249, s[18:19]
	v_mfma_f32_16x16x32_bf16 v[40:43], v[164:167], v[168:171], v[40:43]
	v_mfma_f32_16x16x32_bf16 v[32:35], v[164:167], v[172:175], v[32:35]
	v_mfma_f32_16x16x32_bf16 v[24:27], v[164:167], v[178:181], v[24:27]
	s_add_i32 m0, s101, 0xa000
	s_nop 0
	global_load_lds_dwordx4 v248, s[18:19]
	v_mfma_f32_16x16x32_bf16 v[16:19], v[164:167], v[182:185], v[16:19]
	s_waitcnt lgkmcnt(4)
	v_mfma_f32_16x16x32_bf16 v[100:103], v[152:155], v[212:215], v[100:103]
	v_mfma_f32_16x16x32_bf16 v[92:95], v[152:155], v[216:219], v[92:95]
	s_add_i32 m0, s101, 0xc000
	s_nop 0
	global_load_lds_dwordx4 v243, s[18:19]
	v_mfma_f32_16x16x32_bf16 v[84:87], v[152:155], v[220:223], v[84:87]
	ds_read_b128 v[168:171], v240 offset:32768
	v_mfma_f32_16x16x32_bf16 v[76:79], v[152:155], v[224:227], v[76:79]
	ds_read_b128 v[172:175], v240 offset:34816
	v_mfma_f32_16x16x32_bf16 v[68:71], v[156:159], v[212:215], v[68:71]
	ds_read_b128 v[178:181], v240 offset:36864
	s_add_i32 m0, s101, 0xe000
	s_nop 0
	global_load_lds_dwordx4 v242, s[18:19]
	v_mfma_f32_16x16x32_bf16 v[60:63], v[156:159], v[216:219], v[60:63]
	ds_read_b128 v[182:185], v240 offset:38912
	v_mfma_f32_16x16x32_bf16 v[52:55], v[156:159], v[220:223], v[52:55]
	v_mfma_f32_16x16x32_bf16 v[44:47], v[156:159], v[224:227], v[44:47]
	v_mfma_f32_16x16x32_bf16 v[36:39], v[160:163], v[212:215], v[36:39]
	v_mfma_f32_16x16x32_bf16 v[28:31], v[160:163], v[216:219], v[28:31]
	v_mfma_f32_16x16x32_bf16 v[20:23], v[160:163], v[220:223], v[20:23]
	v_mfma_f32_16x16x32_bf16 v[12:15], v[160:163], v[224:227], v[12:15]
	v_mfma_f32_16x16x32_bf16 v[8:11], v[164:167], v[212:215], v[8:11]
	v_mfma_f32_16x16x32_bf16 v[4:7], v[164:167], v[216:219], v[4:7]
	v_mfma_f32_16x16x32_bf16 v[0:3], v[164:167], v[220:223], v[0:3]
	v_mfma_f32_16x16x32_bf16 v[108:111], v[164:167], v[224:227], v[108:111]
	s_waitcnt lgkmcnt(0)
	v_mfma_f32_16x16x32_bf16 v[124:127], v[192:195], v[168:171], v[124:127]
	ds_read_b128 v[212:215], v240 offset:40960
	v_mfma_f32_16x16x32_bf16 v[120:123], v[192:195], v[172:175], v[120:123]
	ds_read_b128 v[216:219], v240 offset:43008
	v_mfma_f32_16x16x32_bf16 v[116:119], v[192:195], v[178:181], v[116:119]
	ds_read_b128 v[220:223], v240 offset:45056
	v_mfma_f32_16x16x32_bf16 v[112:115], v[192:195], v[182:185], v[112:115]
	ds_read_b128 v[224:227], v240 offset:47104
	v_mfma_f32_16x16x32_bf16 v[104:107], v[198:201], v[168:171], v[104:107]
	v_mfma_f32_16x16x32_bf16 v[96:99], v[198:201], v[172:175], v[96:99]
	v_mfma_f32_16x16x32_bf16 v[88:91], v[198:201], v[178:181], v[88:91]
	v_mfma_f32_16x16x32_bf16 v[80:83], v[198:201], v[182:185], v[80:83]
	v_mfma_f32_16x16x32_bf16 v[72:75], v[204:207], v[168:171], v[72:75]
	v_mfma_f32_16x16x32_bf16 v[64:67], v[204:207], v[172:175], v[64:67]
	v_mfma_f32_16x16x32_bf16 v[56:59], v[204:207], v[178:181], v[56:59]
	v_mfma_f32_16x16x32_bf16 v[48:51], v[204:207], v[182:185], v[48:51]
	v_mfma_f32_16x16x32_bf16 v[40:43], v[208:211], v[168:171], v[40:43]
	v_mfma_f32_16x16x32_bf16 v[32:35], v[208:211], v[172:175], v[32:35]
	v_mfma_f32_16x16x32_bf16 v[24:27], v[208:211], v[178:181], v[24:27]
	v_mfma_f32_16x16x32_bf16 v[16:19], v[208:211], v[182:185], v[16:19]
	s_waitcnt lgkmcnt(0)
	v_mfma_f32_16x16x32_bf16 v[100:103], v[192:195], v[212:215], v[100:103]
	v_mfma_f32_16x16x32_bf16 v[92:95], v[192:195], v[216:219], v[92:95]
	v_mfma_f32_16x16x32_bf16 v[84:87], v[192:195], v[220:223], v[84:87]
	v_mfma_f32_16x16x32_bf16 v[76:79], v[192:195], v[224:227], v[76:79]
	v_mfma_f32_16x16x32_bf16 v[68:71], v[198:201], v[212:215], v[68:71]
	v_mfma_f32_16x16x32_bf16 v[60:63], v[198:201], v[216:219], v[60:63]
	v_mfma_f32_16x16x32_bf16 v[52:55], v[198:201], v[220:223], v[52:55]
	v_mfma_f32_16x16x32_bf16 v[44:47], v[198:201], v[224:227], v[44:47]
	v_mfma_f32_16x16x32_bf16 v[36:39], v[204:207], v[212:215], v[36:39]
	v_mfma_f32_16x16x32_bf16 v[28:31], v[204:207], v[216:219], v[28:31]
	v_mfma_f32_16x16x32_bf16 v[20:23], v[204:207], v[220:223], v[20:23]
	v_mfma_f32_16x16x32_bf16 v[12:15], v[204:207], v[224:227], v[12:15]
	s_add_u32 s2, s2, 0x80
	s_addc_u32 s3, s3, 0
	s_cmpk_eq_i32 s2, 0x780
	s_mov_b32 s0, s1
	v_mfma_f32_16x16x32_bf16 v[8:11], v[208:211], v[212:215], v[8:11]
	v_mfma_f32_16x16x32_bf16 v[4:7], v[208:211], v[216:219], v[4:7]
	v_mfma_f32_16x16x32_bf16 v[0:3], v[208:211], v[220:223], v[0:3]
	v_mfma_f32_16x16x32_bf16 v[108:111], v[208:211], v[224:227], v[108:111]
	s_cbranch_scc0 .LBB0_659
	s_add_i32 s0, 0, 0x10000
	v_add_u32_e32 v136, s0, v149
	v_add_u32_e32 v137, v136, v147
	s_waitcnt vmcnt(0)
	s_barrier
	ds_read_b128 v[128:131], v137
	ds_read_b128 v[132:135], v137 offset:2048
	ds_read_b128 v[150:153], v137 offset:4096
	ds_read_b128 v[154:157], v137 offset:6144
	v_add_u32_e32 v137, s0, v148
	v_add_u32_e32 v147, v137, v147
	ds_read_b128 v[158:161], v147 offset:32768
	ds_read_b128 v[162:165], v147 offset:34816
	ds_read_b128 v[166:169], v147 offset:36864
	ds_read_b128 v[170:173], v147 offset:38912
	s_waitcnt lgkmcnt(0)
	v_mfma_f32_16x16x32_bf16 v[124:127], v[128:131], v[158:161], v[124:127]
	v_mfma_f32_16x16x32_bf16 v[120:123], v[128:131], v[162:165], v[120:123]
	v_mfma_f32_16x16x32_bf16 v[116:119], v[128:131], v[166:169], v[116:119]
	v_mfma_f32_16x16x32_bf16 v[112:115], v[128:131], v[170:173], v[112:115]
	v_mfma_f32_16x16x32_bf16 v[104:107], v[132:135], v[158:161], v[104:107]
	v_mfma_f32_16x16x32_bf16 v[72:75], v[150:153], v[158:161], v[72:75]
	v_mfma_f32_16x16x32_bf16 v[64:67], v[150:153], v[162:165], v[64:67]
	v_mfma_f32_16x16x32_bf16 v[56:59], v[150:153], v[166:169], v[56:59]
	v_mfma_f32_16x16x32_bf16 v[48:51], v[150:153], v[170:173], v[48:51]
	v_mfma_f32_16x16x32_bf16 v[178:181], v[132:135], v[162:165], v[96:99]
	v_mfma_f32_16x16x32_bf16 v[182:185], v[132:135], v[166:169], v[88:91]
	v_mfma_f32_16x16x32_bf16 v[186:189], v[132:135], v[170:173], v[80:83]
	v_mfma_f32_16x16x32_bf16 v[158:161], v[154:157], v[158:161], v[40:43]
	v_mfma_f32_16x16x32_bf16 v[162:165], v[154:157], v[162:165], v[32:35]
	v_mfma_f32_16x16x32_bf16 v[166:169], v[154:157], v[166:169], v[24:27]
	v_mfma_f32_16x16x32_bf16 v[170:173], v[154:157], v[170:173], v[16:19]
	s_nop 2
	ds_read_b128 v[16:19], v147 offset:40960
	ds_read_b128 v[24:27], v147 offset:43008
	ds_read_b128 v[32:35], v147 offset:45056
	ds_read_b128 v[40:43], v147 offset:47104
	s_waitcnt lgkmcnt(0)
	v_mfma_f32_16x16x32_bf16 v[100:103], v[128:131], v[16:19], v[100:103]
	v_mfma_f32_16x16x32_bf16 v[92:95], v[128:131], v[24:27], v[92:95]
	v_mfma_f32_16x16x32_bf16 v[192:195], v[128:131], v[32:35], v[84:87]
	v_mfma_f32_16x16x32_bf16 v[76:79], v[128:131], v[40:43], v[76:79]
	v_mfma_f32_16x16x32_bf16 v[68:71], v[132:135], v[16:19], v[68:71]
	v_mfma_f32_16x16x32_bf16 v[60:63], v[132:135], v[24:27], v[60:63]
	v_mfma_f32_16x16x32_bf16 v[128:131], v[132:135], v[32:35], v[52:55]
	v_mfma_f32_16x16x32_bf16 v[44:47], v[132:135], v[40:43], v[44:47]
	v_mfma_f32_16x16x32_bf16 v[132:135], v[150:153], v[16:19], v[36:39]
	v_mfma_f32_16x16x32_bf16 v[198:201], v[150:153], v[24:27], v[28:31]
	v_mfma_f32_16x16x32_bf16 v[204:207], v[150:153], v[32:35], v[20:23]
	v_mfma_f32_16x16x32_bf16 v[148:151], v[150:153], v[40:43], v[12:15]
	v_mfma_f32_16x16x32_bf16 v[208:211], v[154:157], v[16:19], v[8:11]
	v_mfma_f32_16x16x32_bf16 v[212:215], v[154:157], v[24:27], v[4:7]
	v_mfma_f32_16x16x32_bf16 v[216:219], v[154:157], v[32:35], v[0:3]
	v_mfma_f32_16x16x32_bf16 v[154:157], v[154:157], v[40:43], v[108:111]
	s_nop 1
	v_add_u32_e32 v0, v136, v146
	v_add_u32_e32 v136, v137, v146
	ds_read_b128 v[108:111], v0
	ds_read_b128 v[220:223], v0 offset:2048
	ds_read_b128 v[224:227], v0 offset:4096
	ds_read_b128 v[228:231], v0 offset:6144
	ds_read_b128 v[0:3], v136 offset:32768
	ds_read_b128 v[4:7], v136 offset:34816
	ds_read_b128 v[232:235], v136 offset:36864
	ds_read_b128 v[236:239], v136 offset:38912
	s_waitcnt lgkmcnt(0)
	v_mfma_f32_16x16x32_bf16 v[88:91], v[108:111], v[0:3], v[124:127]
	v_mfma_f32_16x16x32_bf16 v[96:99], v[108:111], v[4:7], v[120:123]
	v_mfma_f32_16x16x32_bf16 v[80:83], v[108:111], v[232:235], v[116:119]
	v_mfma_f32_16x16x32_bf16 v[84:87], v[108:111], v[236:239], v[112:115]
	v_mfma_f32_16x16x32_bf16 v[40:43], v[220:223], v[0:3], v[104:107]
	v_mfma_f32_16x16x32_bf16 v[52:55], v[220:223], v[4:7], v[178:181]
	v_mfma_f32_16x16x32_bf16 v[32:35], v[220:223], v[232:235], v[182:185]
	v_mfma_f32_16x16x32_bf16 v[36:39], v[220:223], v[236:239], v[186:189]
	v_mfma_f32_16x16x32_bf16 v[24:27], v[224:227], v[0:3], v[72:75]
	v_mfma_f32_16x16x32_bf16 v[28:31], v[224:227], v[4:7], v[64:67]
	v_mfma_f32_16x16x32_bf16 v[16:19], v[224:227], v[232:235], v[56:59]
	v_mfma_f32_16x16x32_bf16 v[20:23], v[224:227], v[236:239], v[48:51]
	v_mfma_f32_16x16x32_bf16 v[8:11], v[228:231], v[0:3], v[158:161]
	v_mfma_f32_16x16x32_bf16 v[12:15], v[228:231], v[4:7], v[162:165]
	v_mfma_f32_16x16x32_bf16 v[0:3], v[228:231], v[232:235], v[166:169]
	v_mfma_f32_16x16x32_bf16 v[4:7], v[228:231], v[236:239], v[170:173]
	ds_read_b128 v[48:51], v136 offset:40960
	ds_read_b128 v[64:67], v136 offset:43008
	ds_read_b128 v[158:161], v136 offset:45056
	ds_read_b128 v[162:165], v136 offset:47104
	s_waitcnt lgkmcnt(0)
	v_mfma_f32_16x16x32_bf16 v[104:107], v[220:223], v[48:51], v[68:71]
	v_cmp_ne_u32_e32 vcc, 0, v138
	v_cmp_eq_u32_e64 s[2:3], 0, v138
	s_waitcnt vmcnt(0)
	v_lshl_or_b32 v68, v140, 2, v141
	v_lshl_add_u32 v69, v139, 2, 0
	v_mfma_f32_16x16x32_bf16 v[120:123], v[108:111], v[48:51], v[100:103]
	v_lshl_add_u32 v152, v68, 9, v69
	v_add_u32_e32 v153, 0x400, v152
	v_add_u32_e32 v147, 0x6000, v152
	v_mfma_f32_16x16x32_bf16 v[124:127], v[108:111], v[64:67], v[92:95]
	v_add_u32_e32 v146, 0x6400, v152
	s_barrier
	v_mfma_f32_16x16x32_bf16 v[112:115], v[108:111], v[158:161], v[192:195]
	v_mfma_f32_16x16x32_bf16 v[116:119], v[108:111], v[162:165], v[76:79]
	v_mfma_f32_16x16x32_bf16 v[108:111], v[220:223], v[64:67], v[60:63]
	v_mfma_f32_16x16x32_bf16 v[92:95], v[220:223], v[158:161], v[128:131]
	v_mfma_f32_16x16x32_bf16 v[100:103], v[220:223], v[162:165], v[44:47]
	v_mfma_f32_16x16x32_bf16 v[56:59], v[224:227], v[48:51], v[132:135]
	v_mfma_f32_16x16x32_bf16 v[60:63], v[224:227], v[64:67], v[198:201]
	v_mfma_f32_16x16x32_bf16 v[44:47], v[224:227], v[158:161], v[204:207]
	v_mfma_f32_16x16x32_bf16 v[72:75], v[224:227], v[162:165], v[148:151]
	v_mfma_f32_16x16x32_bf16 v[48:51], v[228:231], v[48:51], v[208:211]
	s_nop 1
	v_add_u32_e32 v151, 0x2000, v152
	v_add_u32_e32 v150, 0x2400, v152
	v_add_u32_e32 v149, 0x4000, v152
	v_mfma_f32_16x16x32_bf16 v[64:67], v[228:231], v[64:67], v[212:215]
	v_add_u32_e32 v148, 0x4400, v152
	v_mfma_f32_16x16x32_bf16 v[68:71], v[228:231], v[158:161], v[216:219]
	v_mfma_f32_16x16x32_bf16 v[76:79], v[228:231], v[162:165], v[154:157]
	s_and_saveexec_b64 s[0:1], s[2:3]
	s_cbranch_execz .LBB0_662
	ds_write2_b32 v152, v88, v96 offset1:16
	ds_write2_b32 v152, v89, v97 offset0:128 offset1:144
	ds_write2_b32 v153, v90, v98 offset1:16
	ds_write2_b32 v153, v91, v99 offset0:128 offset1:144
	ds_write2_b32 v152, v80, v84 offset0:32 offset1:48
	ds_write2_b32 v152, v81, v85 offset0:160 offset1:176
	ds_write2_b32 v153, v82, v86 offset0:32 offset1:48
	ds_write2_b32 v153, v83, v87 offset0:160 offset1:176
	ds_write2_b32 v152, v120, v124 offset0:64 offset1:80
	ds_write2_b32 v152, v121, v125 offset0:192 offset1:208
	ds_write2_b32 v153, v122, v126 offset0:64 offset1:80
	ds_write2_b32 v153, v123, v127 offset0:192 offset1:208
	ds_write2_b32 v152, v112, v116 offset0:96 offset1:112
	ds_write2_b32 v152, v113, v117 offset0:224 offset1:240
	ds_write2_b32 v153, v114, v118 offset0:96 offset1:112
	ds_write2_b32 v153, v115, v119 offset0:224 offset1:240
	ds_write2_b32 v151, v40, v52 offset1:16
	ds_write2_b32 v151, v41, v53 offset0:128 offset1:144
	ds_write2_b32 v150, v42, v54 offset1:16
	ds_write2_b32 v150, v43, v55 offset0:128 offset1:144
	ds_write2_b32 v151, v32, v36 offset0:32 offset1:48
	ds_write2_b32 v151, v33, v37 offset0:160 offset1:176
	ds_write2_b32 v150, v34, v38 offset0:32 offset1:48
	ds_write2_b32 v150, v35, v39 offset0:160 offset1:176
	ds_write2_b32 v151, v104, v108 offset0:64 offset1:80
	ds_write2_b32 v151, v105, v109 offset0:192 offset1:208
	ds_write2_b32 v150, v106, v110 offset0:64 offset1:80
	ds_write2_b32 v150, v107, v111 offset0:192 offset1:208
	ds_write2_b32 v151, v92, v100 offset0:96 offset1:112
	ds_write2_b32 v151, v93, v101 offset0:224 offset1:240
	ds_write2_b32 v150, v94, v102 offset0:96 offset1:112
	ds_write2_b32 v150, v95, v103 offset0:224 offset1:240
	ds_write2_b32 v149, v24, v28 offset1:16
	ds_write2_b32 v149, v25, v29 offset0:128 offset1:144
	ds_write2_b32 v148, v26, v30 offset1:16
	ds_write2_b32 v148, v27, v31 offset0:128 offset1:144
	ds_write2_b32 v149, v16, v20 offset0:32 offset1:48
	ds_write2_b32 v149, v17, v21 offset0:160 offset1:176
	ds_write2_b32 v148, v18, v22 offset0:32 offset1:48
	ds_write2_b32 v148, v19, v23 offset0:160 offset1:176
	ds_write2_b32 v149, v56, v60 offset0:64 offset1:80
	ds_write2_b32 v149, v57, v61 offset0:192 offset1:208
	ds_write2_b32 v148, v58, v62 offset0:64 offset1:80
	ds_write2_b32 v148, v59, v63 offset0:192 offset1:208
	ds_write2_b32 v149, v44, v72 offset0:96 offset1:112
	ds_write2_b32 v149, v45, v73 offset0:224 offset1:240
	ds_write2_b32 v148, v46, v74 offset0:96 offset1:112
	ds_write2_b32 v148, v47, v75 offset0:224 offset1:240
	ds_write2_b32 v147, v8, v12 offset1:16
	ds_write2_b32 v147, v9, v13 offset0:128 offset1:144
	ds_write2_b32 v146, v10, v14 offset1:16
	ds_write2_b32 v146, v11, v15 offset0:128 offset1:144
	ds_write2_b32 v147, v0, v4 offset0:32 offset1:48
	ds_write2_b32 v147, v1, v5 offset0:160 offset1:176
	ds_write2_b32 v146, v2, v6 offset0:32 offset1:48
	ds_write2_b32 v146, v3, v7 offset0:160 offset1:176
	ds_write2_b32 v147, v48, v64 offset0:64 offset1:80
	ds_write2_b32 v147, v49, v65 offset0:192 offset1:208
	ds_write2_b32 v146, v50, v66 offset0:64 offset1:80
	ds_write2_b32 v146, v51, v67 offset0:192 offset1:208
	ds_write2_b32 v147, v68, v76 offset0:96 offset1:112
	ds_write2_b32 v147, v69, v77 offset0:224 offset1:240
	ds_write2_b32 v146, v70, v78 offset0:96 offset1:112
	ds_write2_b32 v146, v71, v79 offset0:224 offset1:240

.LBB0_1072:
	s_andn2_b64 vcc, exec, s[2:3]
	s_cbranch_vccnz .LBB0_1067
	v_mov_b32_e32 v20, v190
	s_mulk_i32 s31, 0xfe
	v_mov_b32_e32 v1, v177
	v_ashrrev_i32_e32 v12, 3, v20
	v_add3_u32 v8, s31, -1, v12
	v_med3_i32 v0, v8, 0, v203
	v_mul_u32_u24_e32 v176, 0x880, v0
	v_add_u32_e32 v0, 64, v8
	v_med3_i32 v0, v0, 0, v203
	v_mul_u32_u24_e32 v0, 0x880, v0
	v_lshl_add_u64 v[2:3], s[8:9], 0, v[0:1]
	v_add_u32_e32 v1, 0x80, v8
	v_med3_i32 v1, v1, 0, v203
	v_mul_u32_u24_e32 v4, 0x880, v1
	v_add_u32_e32 v1, 0xc0, v8
	v_lshrrev_b32_e32 v21, 4, v20
	v_med3_i32 v1, v1, 0, v203
	v_xor_b32_e32 v18, v21, v20
	v_mul_u32_u24_e32 v8, 0x880, v1
	v_lshl_add_u32 v1, s30, 8, v12
	v_mov_b64_e32 v[14:15], s[12:13]
	v_mad_i64_i32 v[12:13], s[2:3], v1, s78, 0
	v_mad_i64_i32 v[14:15], s[2:3], v1, s78, v[14:15]
	v_lshlrev_b32_e32 v1, 4, v18
	v_mov_b32_e32 v5, v177
	v_mov_b32_e32 v9, v177
	v_and_b32_e32 v139, 15, v20
	v_and_b32_e32 v18, 0x70, v1
	v_bfe_u32 v140, v20, 4, 2
	v_bfe_u32 v1, v20, 1, 3
	v_lshl_add_u64 v[6:7], s[8:9], 0, v[4:5]
	v_lshl_add_u64 v[10:11], s[8:9], 0, v[8:9]
	v_lshlrev_b32_e32 v5, 7, v139
	v_bitop3_b32 v9, v21, v1, 3 bitop3:0x6c
	v_bitop3_b32 v1, v140, v1, 4 bitop3:0x36
	v_lshl_or_b32 v142, v1, 4, v5
	v_ashrrev_i32_e32 v1, 1, v20
	v_lshl_add_u32 v146, v20, 4, 0
	v_lshl_add_u64 v[16:17], s[8:9], 0, v[176:177]
	v_mov_b32_e32 v19, v177
	v_and_b32_e32 v141, 0xffffff80, v1
	v_and_or_b32 v141, v20, 64, v141
	v_readfirstlane_b32 s2, v146
	v_add_u32_e32 v1, 0x2000, v146
	v_lshl_add_u64 v[16:17], v[16:17], 0, v[18:19]
	s_mov_b32 m0, s2
	v_readfirstlane_b32 s2, v1
	v_add_u32_e32 v1, 0x4000, v146
	v_lshl_add_u64 v[2:3], v[2:3], 0, v[18:19]
	global_load_lds_dwordx4 v[16:17], off
	s_mov_b32 m0, s2
	v_readfirstlane_b32 s2, v1
	v_add_u32_e32 v1, 0x6000, v146
	v_lshl_add_u64 v[6:7], v[6:7], 0, v[18:19]
	global_load_lds_dwordx4 v[2:3], off
	s_mov_b32 m0, s2
	v_readfirstlane_b32 s2, v1
	v_add_u32_e32 v1, 0x8000, v146
	v_lshl_add_u64 v[10:11], v[10:11], 0, v[18:19]
	global_load_lds_dwordx4 v[6:7], off
	s_mov_b32 m0, s2
	v_readfirstlane_b32 s2, v1
	v_lshl_add_u64 v[14:15], v[14:15], 0, v[18:19]
	global_load_lds_dwordx4 v[10:11], off
	s_mov_b32 m0, s2
	s_mov_b64 s[2:3], 0x22000
	v_add_u32_e32 v1, 0xa000, v146
	v_lshl_add_u64 v[2:3], v[14:15], 0, s[2:3]
	v_readfirstlane_b32 s2, v1
	global_load_lds_dwordx4 v[14:15], off
	s_mov_b32 m0, s2
	s_mov_b64 s[2:3], 0x44000
	v_add_u32_e32 v1, 0xc000, v146
	global_load_lds_dwordx4 v[2:3], off
	v_lshl_add_u64 v[2:3], v[14:15], 0, s[2:3]
	v_readfirstlane_b32 s2, v1
	s_mov_b32 m0, s2
	s_mov_b64 s[2:3], 0x66000
	v_add_u32_e32 v1, 0xe000, v146
	global_load_lds_dwordx4 v[2:3], off
	v_lshl_add_u64 v[2:3], v[14:15], 0, s[2:3]
	v_readfirstlane_b32 s2, v1
	s_mov_b32 m0, s2
	v_bitop3_b32 v1, v21, 7, v20 bitop3:0x48
	global_load_lds_dwordx4 v[2:3], off
	v_lshl_or_b32 v143, v9, 4, v5
	v_lshlrev_b32_e32 v5, 4, v1
	v_or_b32_e32 v2, v5, v8
	v_mov_b32_e32 v3, v177
	v_bfe_u32 v138, v20, 7, 1
	v_or_b32_e32 v12, v12, v5
	v_lshl_add_u64 v[130:131], s[28:29], 0, v[2:3]
	v_or_b32_e32 v2, v5, v4
	v_or_b32_e32 v0, v5, v0
	v_mov_b32_e32 v1, v177
	v_or_b32_e32 v176, v5, v176
	v_mov_b32_e32 v108, 0
	s_mov_b32 s4, 0
	v_lshlrev_b32_e32 v144, 7, v141
	v_lshlrev_b32_e32 v145, 14, v138
	v_lshl_add_u64 v[128:129], s[10:11], 0, v[12:13]
	v_lshl_add_u64 v[132:133], s[28:29], 0, v[2:3]
	v_lshl_add_u64 v[134:135], s[28:29], 0, v[0:1]
	v_lshl_add_u64 v[136:137], s[28:29], 0, v[176:177]
	s_mov_b64 s[2:3], 0
	v_mov_b32_e32 v109, v108
	v_mov_b32_e32 v110, v108
	v_mov_b32_e32 v111, v108
	v_mov_b32_e32 v0, v108
	v_mov_b32_e32 v1, v108
	v_mov_b32_e32 v2, v108
	v_mov_b32_e32 v3, v108
	v_mov_b32_e32 v4, v108
	v_mov_b32_e32 v5, v108
	v_mov_b32_e32 v6, v108
	v_mov_b32_e32 v7, v108
	v_mov_b32_e32 v8, v108
	v_mov_b32_e32 v9, v108
	v_mov_b32_e32 v10, v108
	v_mov_b32_e32 v11, v108
	v_mov_b32_e32 v16, v108
	v_mov_b32_e32 v17, v108
	v_mov_b32_e32 v18, v108
	v_mov_b32_e32 v19, v108
	v_mov_b32_e32 v24, v108
	v_mov_b32_e32 v25, v108
	v_mov_b32_e32 v26, v108
	v_mov_b32_e32 v27, v108
	v_mov_b32_e32 v32, v108
	v_mov_b32_e32 v33, v108
	v_mov_b32_e32 v34, v108
	v_mov_b32_e32 v35, v108
	v_mov_b32_e32 v40, v108
	v_mov_b32_e32 v41, v108
	v_mov_b32_e32 v42, v108
	v_mov_b32_e32 v43, v108
	v_mov_b32_e32 v12, v108
	v_mov_b32_e32 v13, v108
	v_mov_b32_e32 v14, v108
	v_mov_b32_e32 v15, v108
	v_mov_b32_e32 v20, v108
	v_mov_b32_e32 v21, v108
	v_mov_b32_e32 v22, v108
	v_mov_b32_e32 v23, v108
	v_mov_b32_e32 v28, v108
	v_mov_b32_e32 v29, v108
	v_mov_b32_e32 v30, v108
	v_mov_b32_e32 v31, v108
	v_mov_b32_e32 v36, v108
	v_mov_b32_e32 v37, v108
	v_mov_b32_e32 v38, v108
	v_mov_b32_e32 v39, v108
	v_mov_b32_e32 v48, v108
	v_mov_b32_e32 v49, v108
	v_mov_b32_e32 v50, v108
	v_mov_b32_e32 v51, v108
	v_mov_b32_e32 v56, v108
	v_mov_b32_e32 v57, v108
	v_mov_b32_e32 v58, v108
	v_mov_b32_e32 v59, v108
	v_mov_b32_e32 v64, v108
	v_mov_b32_e32 v65, v108
	v_mov_b32_e32 v66, v108
	v_mov_b32_e32 v67, v108
	v_mov_b32_e32 v72, v108
	v_mov_b32_e32 v73, v108
	v_mov_b32_e32 v74, v108
	v_mov_b32_e32 v75, v108
	v_mov_b32_e32 v44, v108
	v_mov_b32_e32 v45, v108
	v_mov_b32_e32 v46, v108
	v_mov_b32_e32 v47, v108
	v_mov_b32_e32 v52, v108
	v_mov_b32_e32 v53, v108
	v_mov_b32_e32 v54, v108
	v_mov_b32_e32 v55, v108
	v_mov_b32_e32 v60, v108
	v_mov_b32_e32 v61, v108
	v_mov_b32_e32 v62, v108
	v_mov_b32_e32 v63, v108
	v_mov_b32_e32 v68, v108
	v_mov_b32_e32 v69, v108
	v_mov_b32_e32 v70, v108
	v_mov_b32_e32 v71, v108
	v_mov_b32_e32 v80, v108
	v_mov_b32_e32 v81, v108
	v_mov_b32_e32 v82, v108
	v_mov_b32_e32 v83, v108
	v_mov_b32_e32 v88, v108
	v_mov_b32_e32 v89, v108
	v_mov_b32_e32 v90, v108
	v_mov_b32_e32 v91, v108
	v_mov_b32_e32 v96, v108
	v_mov_b32_e32 v97, v108
	v_mov_b32_e32 v98, v108
	v_mov_b32_e32 v99, v108
	v_mov_b32_e32 v104, v108
	v_mov_b32_e32 v105, v108
	v_mov_b32_e32 v106, v108
	v_mov_b32_e32 v107, v108
	v_mov_b32_e32 v76, v108
	v_mov_b32_e32 v77, v108
	v_mov_b32_e32 v78, v108
	v_mov_b32_e32 v79, v108
	v_mov_b32_e32 v84, v108
	v_mov_b32_e32 v85, v108
	v_mov_b32_e32 v86, v108
	v_mov_b32_e32 v87, v108
	v_mov_b32_e32 v92, v108
	v_mov_b32_e32 v93, v108
	v_mov_b32_e32 v94, v108
	v_mov_b32_e32 v95, v108
	v_mov_b32_e32 v100, v108
	v_mov_b32_e32 v101, v108
	v_mov_b32_e32 v102, v108
	v_mov_b32_e32 v103, v108
	v_mov_b32_e32 v112, v108
	v_mov_b32_e32 v113, v108
	v_mov_b32_e32 v114, v108
	v_mov_b32_e32 v115, v108
	v_mov_b32_e32 v116, v108
	v_mov_b32_e32 v117, v108
	v_mov_b32_e32 v118, v108
	v_mov_b32_e32 v119, v108
	v_mov_b32_e32 v120, v108
	v_mov_b32_e32 v121, v108
	v_mov_b32_e32 v122, v108
	v_mov_b32_e32 v123, v108
	v_mov_b32_e32 v124, v108
	v_mov_b32_e32 v125, v108
	v_mov_b32_e32 v126, v108
	v_mov_b32_e32 v127, v108
	v_readlane_b32 s98, v255, 2
	v_readlane_b32 s99, v255, 3
	v_readfirstlane_b32 s100, v146
	s_nop 3
	s_load_dwordx2 s[98:99], s[98:99], 0xf0
	s_waitcnt lgkmcnt(0)
	v_subrev_u32_e32 v254, s98, v136
	v_subrev_u32_e32 v253, s98, v134
	v_subrev_u32_e32 v251, s98, v132
	v_subrev_u32_e32 v250, s98, v130
	v_add_u32_e32 v249, 0x770080, v128
	v_subrev_u32_e32 v249, s98, v249
	v_add_u32_e32 v248, 0x792080, v128
	v_subrev_u32_e32 v248, s98, v248
	v_add_u32_e32 v243, 0x7b4080, v128
	v_subrev_u32_e32 v243, s98, v243
	v_add_u32_e32 v242, 0x7d6080, v128
	v_subrev_u32_e32 v242, s98, v242
.LBB0_1074:
	s_add_i32 s5, s4, 0x10000
	s_and_b32 s40, s5, 0x10000
	s_waitcnt vmcnt(0)
	s_barrier
	s_and_b32 s4, s4, 0x10000
	s_add_i32 s4, s4, 0
	v_add_u32_e32 v147, s4, v144
	v_add_u32_e32 v160, v147, v143
	ds_read_b128 v[148:151], v160
	ds_read_b128 v[152:155], v160 offset:2048
	ds_read_b128 v[156:159], v160 offset:4096
	ds_read_b128 v[170:173], v160 offset:6144
	v_add_u32_e32 v241, v147, v142
	v_add_u32_e32 v160, s4, v145
	v_add_u32_e32 v161, v160, v143
	ds_read_b128 v[178:181], v161 offset:32768
	ds_read_b128 v[182:185], v161 offset:34816
	ds_read_b128 v[186:189], v161 offset:36864
	ds_read_b128 v[192:195], v161 offset:38912
	v_add_u32_e32 v240, v160, v142
	s_add_i32 s101, s100, s40
	s_add_u32 s40, s98, s2
	s_addc_u32 s41, s99, s3
	s_mov_b32 m0, s101
	s_nop 0
	global_load_lds_dwordx4 v254, s[40:41]
	s_waitcnt lgkmcnt(0)
	v_mfma_f32_16x16x32_bf16 v[124:127], v[148:151], v[178:181], v[124:127]
	ds_read_b128 v[216:219], v161 offset:40960
	v_mfma_f32_16x16x32_bf16 v[120:123], v[148:151], v[182:185], v[120:123]
	ds_read_b128 v[220:223], v161 offset:43008
	v_mfma_f32_16x16x32_bf16 v[116:119], v[148:151], v[186:189], v[116:119]
	ds_read_b128 v[224:227], v161 offset:45056
	s_add_i32 m0, s101, 0x2000
	s_nop 0
	global_load_lds_dwordx4 v253, s[40:41]
	v_mfma_f32_16x16x32_bf16 v[112:115], v[148:151], v[192:195], v[112:115]
	ds_read_b128 v[228:231], v161 offset:47104
	v_mfma_f32_16x16x32_bf16 v[104:107], v[152:155], v[178:181], v[104:107]
	ds_read_b128 v[198:201], v241
	v_mfma_f32_16x16x32_bf16 v[96:99], v[152:155], v[182:185], v[96:99]
	ds_read_b128 v[204:207], v241 offset:2048
	s_add_i32 m0, s101, 0x4000
	s_nop 0
	global_load_lds_dwordx4 v251, s[40:41]
	v_mfma_f32_16x16x32_bf16 v[88:91], v[152:155], v[186:189], v[88:91]
	ds_read_b128 v[208:211], v241 offset:4096
	v_mfma_f32_16x16x32_bf16 v[80:83], v[152:155], v[192:195], v[80:83]
	ds_read_b128 v[212:215], v241 offset:6144
	v_mfma_f32_16x16x32_bf16 v[72:75], v[156:159], v[178:181], v[72:75]
	s_add_i32 m0, s101, 0x6000
	s_nop 0
	global_load_lds_dwordx4 v250, s[40:41]
	v_mfma_f32_16x16x32_bf16 v[64:67], v[156:159], v[182:185], v[64:67]
	v_mfma_f32_16x16x32_bf16 v[56:59], v[156:159], v[186:189], v[56:59]
	v_mfma_f32_16x16x32_bf16 v[48:51], v[156:159], v[192:195], v[48:51]
	s_add_i32 m0, s101, 0x8000
	s_nop 0
	global_load_lds_dwordx4 v249, s[40:41]
	v_mfma_f32_16x16x32_bf16 v[40:43], v[170:173], v[178:181], v[40:43]
	v_mfma_f32_16x16x32_bf16 v[32:35], v[170:173], v[182:185], v[32:35]
	v_mfma_f32_16x16x32_bf16 v[24:27], v[170:173], v[186:189], v[24:27]
	s_add_i32 m0, s101, 0xa000
	s_nop 0
	global_load_lds_dwordx4 v248, s[40:41]
	v_mfma_f32_16x16x32_bf16 v[16:19], v[170:173], v[192:195], v[16:19]
	s_waitcnt lgkmcnt(4)
	v_mfma_f32_16x16x32_bf16 v[100:103], v[148:151], v[216:219], v[100:103]
	v_mfma_f32_16x16x32_bf16 v[92:95], v[148:151], v[220:223], v[92:95]
	s_add_i32 m0, s101, 0xc000
	s_nop 0
	global_load_lds_dwordx4 v243, s[40:41]
	v_mfma_f32_16x16x32_bf16 v[84:87], v[148:151], v[224:227], v[84:87]
	ds_read_b128 v[178:181], v240 offset:32768
	v_mfma_f32_16x16x32_bf16 v[76:79], v[148:151], v[228:231], v[76:79]
	ds_read_b128 v[182:185], v240 offset:34816
	v_mfma_f32_16x16x32_bf16 v[68:71], v[152:155], v[216:219], v[68:71]
	ds_read_b128 v[186:189], v240 offset:36864
	s_add_i32 m0, s101, 0xe000
	s_nop 0
	global_load_lds_dwordx4 v242, s[40:41]
	v_mfma_f32_16x16x32_bf16 v[60:63], v[152:155], v[220:223], v[60:63]
	ds_read_b128 v[192:195], v240 offset:38912
	v_mfma_f32_16x16x32_bf16 v[52:55], v[152:155], v[224:227], v[52:55]
	v_mfma_f32_16x16x32_bf16 v[44:47], v[152:155], v[228:231], v[44:47]
	v_mfma_f32_16x16x32_bf16 v[36:39], v[156:159], v[216:219], v[36:39]
	v_mfma_f32_16x16x32_bf16 v[28:31], v[156:159], v[220:223], v[28:31]
	v_mfma_f32_16x16x32_bf16 v[20:23], v[156:159], v[224:227], v[20:23]
	v_mfma_f32_16x16x32_bf16 v[12:15], v[156:159], v[228:231], v[12:15]
	v_mfma_f32_16x16x32_bf16 v[8:11], v[170:173], v[216:219], v[8:11]
	v_mfma_f32_16x16x32_bf16 v[4:7], v[170:173], v[220:223], v[4:7]
	v_mfma_f32_16x16x32_bf16 v[0:3], v[170:173], v[224:227], v[0:3]
	v_mfma_f32_16x16x32_bf16 v[108:111], v[170:173], v[228:231], v[108:111]
	s_waitcnt lgkmcnt(0)
	v_mfma_f32_16x16x32_bf16 v[124:127], v[198:201], v[178:181], v[124:127]
	ds_read_b128 v[216:219], v240 offset:40960
	v_mfma_f32_16x16x32_bf16 v[120:123], v[198:201], v[182:185], v[120:123]
	ds_read_b128 v[220:223], v240 offset:43008
	v_mfma_f32_16x16x32_bf16 v[116:119], v[198:201], v[186:189], v[116:119]
	ds_read_b128 v[224:227], v240 offset:45056
	v_mfma_f32_16x16x32_bf16 v[112:115], v[198:201], v[192:195], v[112:115]
	ds_read_b128 v[228:231], v240 offset:47104
	v_mfma_f32_16x16x32_bf16 v[104:107], v[204:207], v[178:181], v[104:107]
	v_mfma_f32_16x16x32_bf16 v[96:99], v[204:207], v[182:185], v[96:99]
	v_mfma_f32_16x16x32_bf16 v[88:91], v[204:207], v[186:189], v[88:91]
	v_mfma_f32_16x16x32_bf16 v[80:83], v[204:207], v[192:195], v[80:83]
	v_mfma_f32_16x16x32_bf16 v[72:75], v[208:211], v[178:181], v[72:75]
	v_mfma_f32_16x16x32_bf16 v[64:67], v[208:211], v[182:185], v[64:67]
	v_mfma_f32_16x16x32_bf16 v[56:59], v[208:211], v[186:189], v[56:59]
	v_mfma_f32_16x16x32_bf16 v[48:51], v[208:211], v[192:195], v[48:51]
	v_mfma_f32_16x16x32_bf16 v[40:43], v[212:215], v[178:181], v[40:43]
	v_mfma_f32_16x16x32_bf16 v[32:35], v[212:215], v[182:185], v[32:35]
	v_mfma_f32_16x16x32_bf16 v[24:27], v[212:215], v[186:189], v[24:27]
	v_mfma_f32_16x16x32_bf16 v[16:19], v[212:215], v[192:195], v[16:19]
	s_waitcnt lgkmcnt(0)
	v_mfma_f32_16x16x32_bf16 v[100:103], v[198:201], v[216:219], v[100:103]
	v_mfma_f32_16x16x32_bf16 v[92:95], v[198:201], v[220:223], v[92:95]
	v_mfma_f32_16x16x32_bf16 v[84:87], v[198:201], v[224:227], v[84:87]
	v_mfma_f32_16x16x32_bf16 v[76:79], v[198:201], v[228:231], v[76:79]
	v_mfma_f32_16x16x32_bf16 v[68:71], v[204:207], v[216:219], v[68:71]
	v_mfma_f32_16x16x32_bf16 v[60:63], v[204:207], v[220:223], v[60:63]
	v_mfma_f32_16x16x32_bf16 v[52:55], v[204:207], v[224:227], v[52:55]
	v_mfma_f32_16x16x32_bf16 v[44:47], v[204:207], v[228:231], v[44:47]
	v_mfma_f32_16x16x32_bf16 v[36:39], v[208:211], v[216:219], v[36:39]
	v_mfma_f32_16x16x32_bf16 v[28:31], v[208:211], v[220:223], v[28:31]
	v_mfma_f32_16x16x32_bf16 v[20:23], v[208:211], v[224:227], v[20:23]
	v_mfma_f32_16x16x32_bf16 v[12:15], v[208:211], v[228:231], v[12:15]
	s_add_u32 s2, s2, 0x80
	s_addc_u32 s3, s3, 0
	s_cmpk_eq_i32 s2, 0x780
	s_mov_b32 s4, s5
	v_mfma_f32_16x16x32_bf16 v[8:11], v[212:215], v[216:219], v[8:11]
	v_mfma_f32_16x16x32_bf16 v[4:7], v[212:215], v[220:223], v[4:7]
	v_mfma_f32_16x16x32_bf16 v[0:3], v[212:215], v[224:227], v[0:3]
	v_mfma_f32_16x16x32_bf16 v[108:111], v[212:215], v[228:231], v[108:111]
	s_cbranch_scc0 .LBB0_1074
	s_add_i32 s2, 0, 0x10000
	v_add_u32_e32 v136, s2, v145
	v_add_u32_e32 v174, s2, v144
	v_add_u32_e32 v137, v136, v143
	v_add_u32_e32 v143, v174, v143
	s_waitcnt vmcnt(0)
	s_barrier
	ds_read_b128 v[128:131], v137 offset:38912
	ds_read_b128 v[132:135], v137 offset:36864
	ds_read_b128 v[146:149], v137 offset:34816
	ds_read_b128 v[150:153], v137 offset:32768
	ds_read_b128 v[154:157], v143 offset:6144
	ds_read_b128 v[158:161], v143 offset:4096
	ds_read_b128 v[170:173], v143 offset:2048
	ds_read_b128 v[178:181], v143
	s_waitcnt lgkmcnt(0)
	v_mfma_f32_16x16x32_bf16 v[124:127], v[178:181], v[150:153], v[124:127]
	v_mfma_f32_16x16x32_bf16 v[120:123], v[178:181], v[146:149], v[120:123]
	v_mfma_f32_16x16x32_bf16 v[116:119], v[178:181], v[132:135], v[116:119]
	v_mfma_f32_16x16x32_bf16 v[112:115], v[178:181], v[128:131], v[112:115]
	v_mfma_f32_16x16x32_bf16 v[104:107], v[170:173], v[150:153], v[104:107]
	v_mfma_f32_16x16x32_bf16 v[72:75], v[158:161], v[150:153], v[72:75]
	v_mfma_f32_16x16x32_bf16 v[64:67], v[158:161], v[146:149], v[64:67]
	v_mfma_f32_16x16x32_bf16 v[56:59], v[158:161], v[132:135], v[56:59]
	v_mfma_f32_16x16x32_bf16 v[48:51], v[158:161], v[128:131], v[48:51]
	v_mfma_f32_16x16x32_bf16 v[182:185], v[170:173], v[146:149], v[96:99]
	v_mfma_f32_16x16x32_bf16 v[186:189], v[170:173], v[132:135], v[88:91]
	v_mfma_f32_16x16x32_bf16 v[192:195], v[170:173], v[128:131], v[80:83]
	v_mfma_f32_16x16x32_bf16 v[150:153], v[154:157], v[150:153], v[40:43]
	v_mfma_f32_16x16x32_bf16 v[144:147], v[154:157], v[146:149], v[32:35]
	v_mfma_f32_16x16x32_bf16 v[132:135], v[154:157], v[132:135], v[24:27]
	v_mfma_f32_16x16x32_bf16 v[128:131], v[154:157], v[128:131], v[16:19]
	s_nop 2
	ds_read_b128 v[16:19], v137 offset:40960
	ds_read_b128 v[24:27], v137 offset:43008
	ds_read_b128 v[32:35], v137 offset:45056
	ds_read_b128 v[40:43], v137 offset:47104
	s_waitcnt lgkmcnt(0)
	v_mfma_f32_16x16x32_bf16 v[100:103], v[178:181], v[16:19], v[100:103]
	v_mfma_f32_16x16x32_bf16 v[92:95], v[178:181], v[24:27], v[92:95]
	v_mfma_f32_16x16x32_bf16 v[198:201], v[178:181], v[32:35], v[84:87]
	v_mfma_f32_16x16x32_bf16 v[76:79], v[178:181], v[40:43], v[76:79]
	v_mfma_f32_16x16x32_bf16 v[68:71], v[170:173], v[16:19], v[68:71]
	v_mfma_f32_16x16x32_bf16 v[60:63], v[170:173], v[24:27], v[60:63]
	v_mfma_f32_16x16x32_bf16 v[178:181], v[170:173], v[32:35], v[52:55]
	v_mfma_f32_16x16x32_bf16 v[44:47], v[170:173], v[40:43], v[44:47]
	v_mfma_f32_16x16x32_bf16 v[170:173], v[158:161], v[16:19], v[36:39]
	v_mfma_f32_16x16x32_bf16 v[204:207], v[158:161], v[24:27], v[28:31]
	v_mfma_f32_16x16x32_bf16 v[208:211], v[158:161], v[32:35], v[20:23]
	v_mfma_f32_16x16x32_bf16 v[158:161], v[158:161], v[40:43], v[12:15]
	v_mfma_f32_16x16x32_bf16 v[212:215], v[154:157], v[16:19], v[8:11]
	v_mfma_f32_16x16x32_bf16 v[216:219], v[154:157], v[24:27], v[4:7]
	v_mfma_f32_16x16x32_bf16 v[220:223], v[154:157], v[32:35], v[0:3]
	v_mfma_f32_16x16x32_bf16 v[154:157], v[154:157], v[40:43], v[108:111]
	s_nop 1
	v_add_u32_e32 v0, v174, v142
	v_add_u32_e32 v136, v136, v142
	ds_read_b128 v[108:111], v0
	ds_read_b128 v[224:227], v0 offset:2048
	ds_read_b128 v[228:231], v0 offset:4096
	ds_read_b128 v[232:235], v0 offset:6144
	ds_read_b128 v[0:3], v136 offset:32768
	ds_read_b128 v[4:7], v136 offset:34816
	ds_read_b128 v[236:239], v136 offset:36864
	ds_read_b128 v[240:243], v136 offset:38912
	s_waitcnt lgkmcnt(0)
	v_mfma_f32_16x16x32_bf16 v[88:91], v[108:111], v[0:3], v[124:127]
	v_mfma_f32_16x16x32_bf16 v[96:99], v[108:111], v[4:7], v[120:123]
	v_mfma_f32_16x16x32_bf16 v[80:83], v[108:111], v[236:239], v[116:119]
	v_mfma_f32_16x16x32_bf16 v[84:87], v[108:111], v[240:243], v[112:115]
	v_mfma_f32_16x16x32_bf16 v[40:43], v[224:227], v[0:3], v[104:107]
	v_mfma_f32_16x16x32_bf16 v[52:55], v[224:227], v[4:7], v[182:185]
	v_mfma_f32_16x16x32_bf16 v[32:35], v[224:227], v[236:239], v[186:189]
	v_mfma_f32_16x16x32_bf16 v[36:39], v[224:227], v[240:243], v[192:195]
	v_mfma_f32_16x16x32_bf16 v[24:27], v[228:231], v[0:3], v[72:75]
	v_mfma_f32_16x16x32_bf16 v[28:31], v[228:231], v[4:7], v[64:67]
	v_mfma_f32_16x16x32_bf16 v[16:19], v[228:231], v[236:239], v[56:59]
	v_mfma_f32_16x16x32_bf16 v[20:23], v[228:231], v[240:243], v[48:51]
	v_mfma_f32_16x16x32_bf16 v[8:11], v[232:235], v[0:3], v[150:153]
	v_mfma_f32_16x16x32_bf16 v[12:15], v[232:235], v[4:7], v[144:147]
	v_mfma_f32_16x16x32_bf16 v[0:3], v[232:235], v[236:239], v[132:135]
	v_mfma_f32_16x16x32_bf16 v[4:7], v[232:235], v[240:243], v[128:131]
	ds_read_b128 v[48:51], v136 offset:40960
	ds_read_b128 v[64:67], v136 offset:43008
	s_nop 0
	ds_read_b128 v[128:131], v136 offset:45056
	ds_read_b128 v[132:135], v136 offset:47104
	s_waitcnt lgkmcnt(0)
	v_mfma_f32_16x16x32_bf16 v[104:107], v[224:227], v[48:51], v[68:71]
	v_cmp_ne_u32_e32 vcc, 0, v138
	v_cmp_eq_u32_e64 s[2:3], 0, v138
	s_waitcnt vmcnt(0)
	v_lshl_or_b32 v68, v140, 2, v141
	v_lshl_add_u32 v69, v139, 2, 0
	v_mfma_f32_16x16x32_bf16 v[120:123], v[108:111], v[48:51], v[100:103]
	s_barrier
	v_mfma_f32_16x16x32_bf16 v[124:127], v[108:111], v[64:67], v[92:95]
	v_mfma_f32_16x16x32_bf16 v[112:115], v[108:111], v[128:131], v[198:201]
	v_mfma_f32_16x16x32_bf16 v[116:119], v[108:111], v[132:135], v[76:79]
	v_mfma_f32_16x16x32_bf16 v[108:111], v[224:227], v[64:67], v[60:63]
	v_mfma_f32_16x16x32_bf16 v[92:95], v[224:227], v[128:131], v[178:181]
	v_mfma_f32_16x16x32_bf16 v[100:103], v[224:227], v[132:135], v[44:47]
	s_nop 1
	v_lshl_add_u32 v178, v68, 9, v69
	v_add_u32_e32 v179, 0x400, v178
	v_add_u32_e32 v176, 0x2000, v178
	v_mfma_f32_16x16x32_bf16 v[56:59], v[228:231], v[48:51], v[170:173]
	v_add_u32_e32 v175, 0x2400, v178
	v_add_u32_e32 v174, 0x4000, v178
	v_mfma_f32_16x16x32_bf16 v[60:63], v[228:231], v[64:67], v[204:207]
	v_add_u32_e32 v173, 0x4400, v178
	v_add_u32_e32 v172, 0x6000, v178
	v_add_u32_e32 v171, 0x6400, v178
	v_mfma_f32_16x16x32_bf16 v[44:47], v[228:231], v[128:131], v[208:211]
	v_mfma_f32_16x16x32_bf16 v[72:75], v[228:231], v[132:135], v[158:161]
	v_mfma_f32_16x16x32_bf16 v[48:51], v[232:235], v[48:51], v[212:215]
	v_mfma_f32_16x16x32_bf16 v[64:67], v[232:235], v[64:67], v[216:219]
	v_mfma_f32_16x16x32_bf16 v[68:71], v[232:235], v[128:131], v[220:223]
	v_mfma_f32_16x16x32_bf16 v[76:79], v[232:235], v[132:135], v[154:157]
	s_and_saveexec_b64 s[4:5], s[2:3]
	s_cbranch_execz .LBB0_1077
	ds_write2_b32 v178, v88, v96 offset1:16
	ds_write2_b32 v178, v89, v97 offset0:128 offset1:144
	ds_write2_b32 v179, v90, v98 offset1:16
	ds_write2_b32 v179, v91, v99 offset0:128 offset1:144
	ds_write2_b32 v178, v80, v84 offset0:32 offset1:48
	ds_write2_b32 v178, v81, v85 offset0:160 offset1:176
	ds_write2_b32 v179, v82, v86 offset0:32 offset1:48
	ds_write2_b32 v179, v83, v87 offset0:160 offset1:176
	ds_write2_b32 v178, v120, v124 offset0:64 offset1:80
	ds_write2_b32 v178, v121, v125 offset0:192 offset1:208
	ds_write2_b32 v179, v122, v126 offset0:64 offset1:80
	ds_write2_b32 v179, v123, v127 offset0:192 offset1:208
	ds_write2_b32 v178, v112, v116 offset0:96 offset1:112
	ds_write2_b32 v178, v113, v117 offset0:224 offset1:240
	ds_write2_b32 v179, v114, v118 offset0:96 offset1:112
	ds_write2_b32 v179, v115, v119 offset0:224 offset1:240
	ds_write2_b32 v176, v40, v52 offset1:16
	ds_write2_b32 v176, v41, v53 offset0:128 offset1:144
	ds_write2_b32 v175, v42, v54 offset1:16
	ds_write2_b32 v175, v43, v55 offset0:128 offset1:144
	ds_write2_b32 v176, v32, v36 offset0:32 offset1:48
	ds_write2_b32 v176, v33, v37 offset0:160 offset1:176
	ds_write2_b32 v175, v34, v38 offset0:32 offset1:48
	ds_write2_b32 v175, v35, v39 offset0:160 offset1:176
	ds_write2_b32 v176, v104, v108 offset0:64 offset1:80
	ds_write2_b32 v176, v105, v109 offset0:192 offset1:208
	ds_write2_b32 v175, v106, v110 offset0:64 offset1:80
	ds_write2_b32 v175, v107, v111 offset0:192 offset1:208
	ds_write2_b32 v176, v92, v100 offset0:96 offset1:112
	ds_write2_b32 v176, v93, v101 offset0:224 offset1:240
	ds_write2_b32 v175, v94, v102 offset0:96 offset1:112
	ds_write2_b32 v175, v95, v103 offset0:224 offset1:240
	ds_write2_b32 v174, v24, v28 offset1:16
	ds_write2_b32 v174, v25, v29 offset0:128 offset1:144
	ds_write2_b32 v173, v26, v30 offset1:16
	ds_write2_b32 v173, v27, v31 offset0:128 offset1:144
	ds_write2_b32 v174, v16, v20 offset0:32 offset1:48
	ds_write2_b32 v174, v17, v21 offset0:160 offset1:176
	ds_write2_b32 v173, v18, v22 offset0:32 offset1:48
	ds_write2_b32 v173, v19, v23 offset0:160 offset1:176
	ds_write2_b32 v174, v56, v60 offset0:64 offset1:80
	ds_write2_b32 v174, v57, v61 offset0:192 offset1:208
	ds_write2_b32 v173, v58, v62 offset0:64 offset1:80
	ds_write2_b32 v173, v59, v63 offset0:192 offset1:208
	ds_write2_b32 v174, v44, v72 offset0:96 offset1:112
	ds_write2_b32 v174, v45, v73 offset0:224 offset1:240
	ds_write2_b32 v173, v46, v74 offset0:96 offset1:112
	ds_write2_b32 v173, v47, v75 offset0:224 offset1:240
	ds_write2_b32 v172, v8, v12 offset1:16
	ds_write2_b32 v172, v9, v13 offset0:128 offset1:144
	ds_write2_b32 v171, v10, v14 offset1:16
	ds_write2_b32 v171, v11, v15 offset0:128 offset1:144
	ds_write2_b32 v172, v0, v4 offset0:32 offset1:48
	ds_write2_b32 v172, v1, v5 offset0:160 offset1:176
	ds_write2_b32 v171, v2, v6 offset0:32 offset1:48
	ds_write2_b32 v171, v3, v7 offset0:160 offset1:176
	ds_write2_b32 v172, v48, v64 offset0:64 offset1:80
	ds_write2_b32 v172, v49, v65 offset0:192 offset1:208
	ds_write2_b32 v171, v50, v66 offset0:64 offset1:80
	ds_write2_b32 v171, v51, v67 offset0:192 offset1:208
	ds_write2_b32 v172, v68, v76 offset0:96 offset1:112
	ds_write2_b32 v172, v69, v77 offset0:224 offset1:240
	ds_write2_b32 v171, v70, v78 offset0:96 offset1:112
	ds_write2_b32 v171, v71, v79 offset0:224 offset1:240

.LBB0_1142:
	s_ashr_i32 s10, s2, 7
	s_mul_i32 s3, s10, 33
	s_bfe_u32 s11, s2, 0x50002
	s_add_i32 s13, s3, s11
	s_add_i32 s13, s13, 1
	v_mov_b32_e32 v14, v190
	s_lshl_b32 s17, s13, 8
	s_lshl_b32 s2, s2, 8
	s_and_b32 s12, s2, 0x300
	v_ashrrev_i32_e32 v15, 3, v14
	v_lshrrev_b32_e32 v16, 4, v14
	v_add_u32_e32 v18, s17, v15
	v_xor_b32_e32 v17, v16, v14
	v_add_u32_e32 v2, 64, v18
	v_mov_b64_e32 v[0:1], s[46:47]
	v_add_u32_e32 v4, 0x80, v18
	v_add_u32_e32 v6, 0xc0, v18
	v_add_u32_e32 v12, s12, v15
	v_mov_b64_e32 v[10:11], s[40:41]
	v_mad_i64_i32 v[2:3], s[2:3], v2, s87, v[0:1]
	v_mad_i64_i32 v[4:5], s[2:3], v4, s87, v[0:1]
	v_mad_i64_i32 v[6:7], s[2:3], v6, s87, v[0:1]
	v_mad_i64_i32 v[8:9], s[2:3], v12, s87, 0
	v_mad_i64_i32 v[10:11], s[2:3], v12, s87, v[10:11]
	v_mad_i64_i32 v[12:13], s[2:3], v18, s87, 0
	v_mad_i64_i32 v[0:1], s[2:3], v18, s87, v[0:1]
	v_lshlrev_b32_e32 v17, 4, v17
	v_lshl_add_u32 v150, v14, 4, 0
	v_and_b32_e32 v176, 0x70, v17
	v_readfirstlane_b32 s2, v150
	v_lshl_add_u64 v[0:1], v[0:1], 0, v[176:177]
	s_mov_b32 m0, s2
	v_lshl_add_u64 v[2:3], v[2:3], 0, v[176:177]
	global_load_lds_dwordx4 v[0:1], off
	v_add_u32_e32 v0, 0x2000, v150
	v_lshl_add_u64 v[4:5], v[4:5], 0, v[176:177]
	v_readfirstlane_b32 s2, v0
	v_add_u32_e32 v0, 0x4000, v150
	s_mov_b32 m0, s2
	v_readfirstlane_b32 s2, v0
	v_add_u32_e32 v0, 0x6000, v150
	global_load_lds_dwordx4 v[2:3], off
	s_mov_b32 m0, s2
	v_readfirstlane_b32 s2, v0
	v_add_u32_e32 v0, 0x8000, v150
	v_lshl_add_u64 v[6:7], v[6:7], 0, v[176:177]
	global_load_lds_dwordx4 v[4:5], off
	s_mov_b32 m0, s2
	v_readfirstlane_b32 s2, v0
	v_lshl_add_u64 v[10:11], v[10:11], 0, v[176:177]
	global_load_lds_dwordx4 v[6:7], off
	s_mov_b32 m0, s2
	s_mov_b64 s[2:3], 0x58000
	v_add_u32_e32 v2, 0xa000, v150
	v_lshl_add_u64 v[0:1], v[10:11], 0, s[2:3]
	v_readfirstlane_b32 s2, v2
	global_load_lds_dwordx4 v[10:11], off
	s_mov_b32 m0, s2
	s_mov_b64 s[2:3], 0xb0000
	v_add_u32_e32 v2, 0xc000, v150
	global_load_lds_dwordx4 v[0:1], off
	v_lshl_add_u64 v[0:1], v[10:11], 0, s[2:3]
	v_readfirstlane_b32 s2, v2
	s_mov_b32 m0, s2
	s_mov_b64 s[2:3], 0x108000
	v_add_u32_e32 v2, 0xe000, v150
	global_load_lds_dwordx4 v[0:1], off
	v_lshl_add_u64 v[0:1], v[10:11], 0, s[2:3]
	v_readfirstlane_b32 s2, v2
	s_mov_b32 m0, s2
	s_mulk_i32 s10, 0x2100
	global_load_lds_dwordx4 v[0:1], off
	s_lshl_b32 s18, s11, 8
	s_add_i32 s18, s18, s10
	v_bitop3_b32 v0, v16, 7, v14 bitop3:0x48
	v_add_u32_e32 v3, s18, v15
	v_lshlrev_b32_e32 v2, 4, v0
	v_add_u32_e32 v0, 0x140, v3
	v_mad_i64_i32 v[0:1], s[2:3], v0, s87, 0
	v_or_b32_e32 v0, v0, v2
	v_lshl_add_u64 v[130:131], s[50:51], 0, v[0:1]
	v_add_u32_e32 v0, 0x180, v3
	v_mad_i64_i32 v[0:1], s[2:3], v0, s87, 0
	v_and_b32_e32 v139, 15, v14
	v_bfe_u32 v140, v14, 4, 2
	v_bfe_u32 v17, v14, 1, 3
	v_or_b32_e32 v0, v0, v2
	v_lshlrev_b32_e32 v18, 7, v139
	v_bitop3_b32 v19, v16, v17, 3 bitop3:0x6c
	v_bitop3_b32 v17, v140, v17, 4 bitop3:0x36
	v_lshl_add_u64 v[132:133], s[50:51], 0, v[0:1]
	v_add_u32_e32 v0, 0x1c0, v3
	v_lshl_or_b32 v146, v17, 4, v18
	v_ashrrev_i32_e32 v17, 1, v14
	v_mad_i64_i32 v[0:1], s[2:3], v0, s87, 0
	v_bfe_u32 v138, v14, 7, 1
	v_and_b32_e32 v141, 0xffffff80, v17
	v_and_or_b32 v141, v14, 64, v141
	v_or_b32_e32 v12, v12, v2
	v_or_b32_e32 v0, v0, v2
	v_or_b32_e32 v8, v8, v2
	v_mov_b32_e32 v108, 0
	v_lshl_or_b32 v147, v19, 4, v18
	v_lshlrev_b32_e32 v149, 7, v141
	v_lshlrev_b32_e32 v148, 14, v138
	v_lshl_add_u64 v[128:129], s[50:51], 0, v[12:13]
	v_lshl_add_u64 v[134:135], s[50:51], 0, v[0:1]
	v_lshl_add_u64 v[136:137], s[8:9], 0, v[8:9]
	s_mov_b64 s[2:3], 0
	s_mov_b32 s10, 0
	v_mov_b32_e32 v109, v108
	v_mov_b32_e32 v110, v108
	v_mov_b32_e32 v111, v108
	v_mov_b32_e32 v0, v108
	v_mov_b32_e32 v1, v108
	v_mov_b32_e32 v2, v108
	v_mov_b32_e32 v3, v108
	v_mov_b32_e32 v4, v108
	v_mov_b32_e32 v5, v108
	v_mov_b32_e32 v6, v108
	v_mov_b32_e32 v7, v108
	v_mov_b32_e32 v8, v108
	v_mov_b32_e32 v9, v108
	v_mov_b32_e32 v10, v108
	v_mov_b32_e32 v11, v108
	v_mov_b32_e32 v16, v108
	v_mov_b32_e32 v17, v108
	v_mov_b32_e32 v18, v108
	v_mov_b32_e32 v19, v108
	v_mov_b32_e32 v24, v108
	v_mov_b32_e32 v25, v108
	v_mov_b32_e32 v26, v108
	v_mov_b32_e32 v27, v108
	v_mov_b32_e32 v32, v108
	v_mov_b32_e32 v33, v108
	v_mov_b32_e32 v34, v108
	v_mov_b32_e32 v35, v108
	v_mov_b32_e32 v40, v108
	v_mov_b32_e32 v41, v108
	v_mov_b32_e32 v42, v108
	v_mov_b32_e32 v43, v108
	v_mov_b32_e32 v12, v108
	v_mov_b32_e32 v13, v108
	v_mov_b32_e32 v14, v108
	v_mov_b32_e32 v15, v108
	v_mov_b32_e32 v20, v108
	v_mov_b32_e32 v21, v108
	v_mov_b32_e32 v22, v108
	v_mov_b32_e32 v23, v108
	v_mov_b32_e32 v28, v108
	v_mov_b32_e32 v29, v108
	v_mov_b32_e32 v30, v108
	v_mov_b32_e32 v31, v108
	v_mov_b32_e32 v36, v108
	v_mov_b32_e32 v37, v108
	v_mov_b32_e32 v38, v108
	v_mov_b32_e32 v39, v108
	v_mov_b32_e32 v48, v108
	v_mov_b32_e32 v49, v108
	v_mov_b32_e32 v50, v108
	v_mov_b32_e32 v51, v108
	v_mov_b32_e32 v56, v108
	v_mov_b32_e32 v57, v108
	v_mov_b32_e32 v58, v108
	v_mov_b32_e32 v59, v108
	v_mov_b32_e32 v64, v108
	v_mov_b32_e32 v65, v108
	v_mov_b32_e32 v66, v108
	v_mov_b32_e32 v67, v108
	v_mov_b32_e32 v72, v108
	v_mov_b32_e32 v73, v108
	v_mov_b32_e32 v74, v108
	v_mov_b32_e32 v75, v108
	v_mov_b32_e32 v44, v108
	v_mov_b32_e32 v45, v108
	v_mov_b32_e32 v46, v108
	v_mov_b32_e32 v47, v108
	v_mov_b32_e32 v52, v108
	v_mov_b32_e32 v53, v108
	v_mov_b32_e32 v54, v108
	v_mov_b32_e32 v55, v108
	v_mov_b32_e32 v60, v108
	v_mov_b32_e32 v61, v108
	v_mov_b32_e32 v62, v108
	v_mov_b32_e32 v63, v108
	v_mov_b32_e32 v68, v108
	v_mov_b32_e32 v69, v108
	v_mov_b32_e32 v70, v108
	v_mov_b32_e32 v71, v108
	v_mov_b32_e32 v80, v108
	v_mov_b32_e32 v81, v108
	v_mov_b32_e32 v82, v108
	v_mov_b32_e32 v83, v108
	v_mov_b32_e32 v88, v108
	v_mov_b32_e32 v89, v108
	v_mov_b32_e32 v90, v108
	v_mov_b32_e32 v91, v108
	v_mov_b32_e32 v96, v108
	v_mov_b32_e32 v97, v108
	v_mov_b32_e32 v98, v108
	v_mov_b32_e32 v99, v108
	v_mov_b32_e32 v104, v108
	v_mov_b32_e32 v105, v108
	v_mov_b32_e32 v106, v108
	v_mov_b32_e32 v107, v108
	v_mov_b32_e32 v76, v108
	v_mov_b32_e32 v77, v108
	v_mov_b32_e32 v78, v108
	v_mov_b32_e32 v79, v108
	v_mov_b32_e32 v84, v108
	v_mov_b32_e32 v85, v108
	v_mov_b32_e32 v86, v108
	v_mov_b32_e32 v87, v108
	v_mov_b32_e32 v92, v108
	v_mov_b32_e32 v93, v108
	v_mov_b32_e32 v94, v108
	v_mov_b32_e32 v95, v108
	v_mov_b32_e32 v100, v108
	v_mov_b32_e32 v101, v108
	v_mov_b32_e32 v102, v108
	v_mov_b32_e32 v103, v108
	v_mov_b32_e32 v112, v108
	v_mov_b32_e32 v113, v108
	v_mov_b32_e32 v114, v108
	v_mov_b32_e32 v115, v108
	v_mov_b32_e32 v116, v108
	v_mov_b32_e32 v117, v108
	v_mov_b32_e32 v118, v108
	v_mov_b32_e32 v119, v108
	v_mov_b32_e32 v120, v108
	v_mov_b32_e32 v121, v108
	v_mov_b32_e32 v122, v108
	v_mov_b32_e32 v123, v108
	v_mov_b32_e32 v124, v108
	v_mov_b32_e32 v125, v108
	v_mov_b32_e32 v126, v108
	v_mov_b32_e32 v127, v108
	v_readlane_b32 s98, v255, 2
	v_readlane_b32 s99, v255, 3
	v_readfirstlane_b32 s100, v150
	s_nop 3
	s_load_dwordx2 s[98:99], s[98:99], 0xf0
	s_waitcnt lgkmcnt(0)
	v_subrev_u32_e32 v254, s98, v128
	v_subrev_u32_e32 v253, s98, v130
	v_subrev_u32_e32 v251, s98, v132
	v_subrev_u32_e32 v250, s98, v134
	v_add_u32_e32 v249, 0x1320080, v136
	v_subrev_u32_e32 v249, s98, v249
	v_add_u32_e32 v248, 0x1378080, v136
	v_subrev_u32_e32 v248, s98, v248
	v_add_u32_e32 v243, 0x13d0080, v136
	v_subrev_u32_e32 v243, s98, v243
	v_add_u32_e32 v242, 0x1428080, v136
	v_subrev_u32_e32 v242, s98, v242
.LBB0_1143:
	s_add_i32 s11, s10, 0x10000
	s_and_b32 s19, s11, 0x10000
	s_waitcnt vmcnt(0)
	s_barrier
	s_and_b32 s10, s10, 0x10000
	s_add_i32 s10, s10, 0
	v_add_u32_e32 v151, s10, v149
	v_add_u32_e32 v164, v151, v147
	ds_read_b128 v[152:155], v164
	ds_read_b128 v[156:159], v164 offset:2048
	ds_read_b128 v[160:163], v164 offset:4096
	ds_read_b128 v[164:167], v164 offset:6144
	v_add_u32_e32 v241, v151, v146
	v_add_u32_e32 v176, s10, v148
	v_add_u32_e32 v186, v176, v147
	ds_read_b128 v[168:171], v186 offset:32768
	ds_read_b128 v[172:175], v186 offset:34816
	ds_read_b128 v[178:181], v186 offset:36864
	ds_read_b128 v[182:185], v186 offset:38912
	v_add_u32_e32 v240, v176, v146
	s_add_i32 s101, s100, s19
	s_add_u32 s20, s98, s2
	s_addc_u32 s21, s99, s3
	s_mov_b32 m0, s101
	s_nop 0
	global_load_lds_dwordx4 v254, s[20:21]
	s_waitcnt lgkmcnt(0)
	v_mfma_f32_16x16x32_bf16 v[124:127], v[152:155], v[168:171], v[124:127]
	ds_read_b128 v[212:215], v186 offset:40960
	v_mfma_f32_16x16x32_bf16 v[120:123], v[152:155], v[172:175], v[120:123]
	ds_read_b128 v[216:219], v186 offset:43008
	v_mfma_f32_16x16x32_bf16 v[116:119], v[152:155], v[178:181], v[116:119]
	ds_read_b128 v[220:223], v186 offset:45056
	s_add_i32 m0, s101, 0x2000
	s_nop 0
	global_load_lds_dwordx4 v253, s[20:21]
	v_mfma_f32_16x16x32_bf16 v[112:115], v[152:155], v[182:185], v[112:115]
	ds_read_b128 v[224:227], v186 offset:47104
	v_mfma_f32_16x16x32_bf16 v[104:107], v[156:159], v[168:171], v[104:107]
	ds_read_b128 v[192:195], v241
	v_mfma_f32_16x16x32_bf16 v[96:99], v[156:159], v[172:175], v[96:99]
	ds_read_b128 v[198:201], v241 offset:2048
	s_add_i32 m0, s101, 0x4000
	s_nop 0
	global_load_lds_dwordx4 v251, s[20:21]
	v_mfma_f32_16x16x32_bf16 v[88:91], v[156:159], v[178:181], v[88:91]
	ds_read_b128 v[204:207], v241 offset:4096
	v_mfma_f32_16x16x32_bf16 v[80:83], v[156:159], v[182:185], v[80:83]
	ds_read_b128 v[208:211], v241 offset:6144
	v_mfma_f32_16x16x32_bf16 v[72:75], v[160:163], v[168:171], v[72:75]
	s_add_i32 m0, s101, 0x6000
	s_nop 0
	global_load_lds_dwordx4 v250, s[20:21]
	v_mfma_f32_16x16x32_bf16 v[64:67], v[160:163], v[172:175], v[64:67]
	v_mfma_f32_16x16x32_bf16 v[56:59], v[160:163], v[178:181], v[56:59]
	v_mfma_f32_16x16x32_bf16 v[48:51], v[160:163], v[182:185], v[48:51]
	s_add_i32 m0, s101, 0x8000
	s_nop 0
	global_load_lds_dwordx4 v249, s[20:21]
	v_mfma_f32_16x16x32_bf16 v[40:43], v[164:167], v[168:171], v[40:43]
	v_mfma_f32_16x16x32_bf16 v[32:35], v[164:167], v[172:175], v[32:35]
	v_mfma_f32_16x16x32_bf16 v[24:27], v[164:167], v[178:181], v[24:27]
	s_add_i32 m0, s101, 0xa000
	s_nop 0
	global_load_lds_dwordx4 v248, s[20:21]
	v_mfma_f32_16x16x32_bf16 v[16:19], v[164:167], v[182:185], v[16:19]
	s_waitcnt lgkmcnt(4)
	v_mfma_f32_16x16x32_bf16 v[100:103], v[152:155], v[212:215], v[100:103]
	v_mfma_f32_16x16x32_bf16 v[92:95], v[152:155], v[216:219], v[92:95]
	s_add_i32 m0, s101, 0xc000
	s_nop 0
	global_load_lds_dwordx4 v243, s[20:21]
	v_mfma_f32_16x16x32_bf16 v[84:87], v[152:155], v[220:223], v[84:87]
	ds_read_b128 v[168:171], v240 offset:32768
	v_mfma_f32_16x16x32_bf16 v[76:79], v[152:155], v[224:227], v[76:79]
	ds_read_b128 v[172:175], v240 offset:34816
	v_mfma_f32_16x16x32_bf16 v[68:71], v[156:159], v[212:215], v[68:71]
	ds_read_b128 v[178:181], v240 offset:36864
	s_add_i32 m0, s101, 0xe000
	s_nop 0
	global_load_lds_dwordx4 v242, s[20:21]
	v_mfma_f32_16x16x32_bf16 v[60:63], v[156:159], v[216:219], v[60:63]
	ds_read_b128 v[182:185], v240 offset:38912
	v_mfma_f32_16x16x32_bf16 v[52:55], v[156:159], v[220:223], v[52:55]
	v_mfma_f32_16x16x32_bf16 v[44:47], v[156:159], v[224:227], v[44:47]
	v_mfma_f32_16x16x32_bf16 v[36:39], v[160:163], v[212:215], v[36:39]
	v_mfma_f32_16x16x32_bf16 v[28:31], v[160:163], v[216:219], v[28:31]
	v_mfma_f32_16x16x32_bf16 v[20:23], v[160:163], v[220:223], v[20:23]
	v_mfma_f32_16x16x32_bf16 v[12:15], v[160:163], v[224:227], v[12:15]
	v_mfma_f32_16x16x32_bf16 v[8:11], v[164:167], v[212:215], v[8:11]
	v_mfma_f32_16x16x32_bf16 v[4:7], v[164:167], v[216:219], v[4:7]
	v_mfma_f32_16x16x32_bf16 v[0:3], v[164:167], v[220:223], v[0:3]
	v_mfma_f32_16x16x32_bf16 v[108:111], v[164:167], v[224:227], v[108:111]
	s_waitcnt lgkmcnt(0)
	v_mfma_f32_16x16x32_bf16 v[124:127], v[192:195], v[168:171], v[124:127]
	ds_read_b128 v[212:215], v240 offset:40960
	v_mfma_f32_16x16x32_bf16 v[120:123], v[192:195], v[172:175], v[120:123]
	ds_read_b128 v[216:219], v240 offset:43008
	v_mfma_f32_16x16x32_bf16 v[116:119], v[192:195], v[178:181], v[116:119]
	ds_read_b128 v[220:223], v240 offset:45056
	v_mfma_f32_16x16x32_bf16 v[112:115], v[192:195], v[182:185], v[112:115]
	ds_read_b128 v[224:227], v240 offset:47104
	v_mfma_f32_16x16x32_bf16 v[104:107], v[198:201], v[168:171], v[104:107]
	v_mfma_f32_16x16x32_bf16 v[96:99], v[198:201], v[172:175], v[96:99]
	v_mfma_f32_16x16x32_bf16 v[88:91], v[198:201], v[178:181], v[88:91]
	v_mfma_f32_16x16x32_bf16 v[80:83], v[198:201], v[182:185], v[80:83]
	v_mfma_f32_16x16x32_bf16 v[72:75], v[204:207], v[168:171], v[72:75]
	v_mfma_f32_16x16x32_bf16 v[64:67], v[204:207], v[172:175], v[64:67]
	v_mfma_f32_16x16x32_bf16 v[56:59], v[204:207], v[178:181], v[56:59]
	v_mfma_f32_16x16x32_bf16 v[48:51], v[204:207], v[182:185], v[48:51]
	v_mfma_f32_16x16x32_bf16 v[40:43], v[208:211], v[168:171], v[40:43]
	v_mfma_f32_16x16x32_bf16 v[32:35], v[208:211], v[172:175], v[32:35]
	v_mfma_f32_16x16x32_bf16 v[24:27], v[208:211], v[178:181], v[24:27]
	v_mfma_f32_16x16x32_bf16 v[16:19], v[208:211], v[182:185], v[16:19]
	s_waitcnt lgkmcnt(0)
	v_mfma_f32_16x16x32_bf16 v[100:103], v[192:195], v[212:215], v[100:103]
	v_mfma_f32_16x16x32_bf16 v[92:95], v[192:195], v[216:219], v[92:95]
	v_mfma_f32_16x16x32_bf16 v[84:87], v[192:195], v[220:223], v[84:87]
	v_mfma_f32_16x16x32_bf16 v[76:79], v[192:195], v[224:227], v[76:79]
	v_mfma_f32_16x16x32_bf16 v[68:71], v[198:201], v[212:215], v[68:71]
	v_mfma_f32_16x16x32_bf16 v[60:63], v[198:201], v[216:219], v[60:63]
	v_mfma_f32_16x16x32_bf16 v[52:55], v[198:201], v[220:223], v[52:55]
	v_mfma_f32_16x16x32_bf16 v[44:47], v[198:201], v[224:227], v[44:47]
	v_mfma_f32_16x16x32_bf16 v[36:39], v[204:207], v[212:215], v[36:39]
	v_mfma_f32_16x16x32_bf16 v[28:31], v[204:207], v[216:219], v[28:31]
	v_mfma_f32_16x16x32_bf16 v[20:23], v[204:207], v[220:223], v[20:23]
	v_mfma_f32_16x16x32_bf16 v[12:15], v[204:207], v[224:227], v[12:15]
	s_add_u32 s2, s2, 0x80
	s_addc_u32 s3, s3, 0
	s_cmpk_eq_i32 s2, 0x1580
	s_mov_b32 s10, s11
	v_mfma_f32_16x16x32_bf16 v[8:11], v[208:211], v[212:215], v[8:11]
	v_mfma_f32_16x16x32_bf16 v[4:7], v[208:211], v[216:219], v[4:7]
	v_mfma_f32_16x16x32_bf16 v[0:3], v[208:211], v[220:223], v[0:3]
	v_mfma_f32_16x16x32_bf16 v[108:111], v[208:211], v[224:227], v[108:111]
	s_cbranch_scc0 .LBB0_1143
	s_add_i32 s2, 0, 0x10000
	v_add_u32_e32 v136, s2, v149
	v_add_u32_e32 v137, v136, v147
	s_waitcnt vmcnt(0)
	s_barrier
	ds_read_b128 v[128:131], v137
	ds_read_b128 v[132:135], v137 offset:2048
	ds_read_b128 v[150:153], v137 offset:4096
	ds_read_b128 v[154:157], v137 offset:6144
	v_add_u32_e32 v137, s2, v148
	v_add_u32_e32 v147, v137, v147
	ds_read_b128 v[158:161], v147 offset:32768
	ds_read_b128 v[162:165], v147 offset:34816
	ds_read_b128 v[166:169], v147 offset:36864
	ds_read_b128 v[170:173], v147 offset:38912
	s_waitcnt lgkmcnt(0)
	v_mfma_f32_16x16x32_bf16 v[124:127], v[128:131], v[158:161], v[124:127]
	v_mfma_f32_16x16x32_bf16 v[120:123], v[128:131], v[162:165], v[120:123]
	v_mfma_f32_16x16x32_bf16 v[116:119], v[128:131], v[166:169], v[116:119]
	v_mfma_f32_16x16x32_bf16 v[112:115], v[128:131], v[170:173], v[112:115]
	v_mfma_f32_16x16x32_bf16 v[104:107], v[132:135], v[158:161], v[104:107]
	v_mfma_f32_16x16x32_bf16 v[72:75], v[150:153], v[158:161], v[72:75]
	v_mfma_f32_16x16x32_bf16 v[64:67], v[150:153], v[162:165], v[64:67]
	v_mfma_f32_16x16x32_bf16 v[56:59], v[150:153], v[166:169], v[56:59]
	v_mfma_f32_16x16x32_bf16 v[48:51], v[150:153], v[170:173], v[48:51]
	v_mfma_f32_16x16x32_bf16 v[178:181], v[132:135], v[162:165], v[96:99]
	v_mfma_f32_16x16x32_bf16 v[182:185], v[132:135], v[166:169], v[88:91]
	v_mfma_f32_16x16x32_bf16 v[186:189], v[132:135], v[170:173], v[80:83]
	v_mfma_f32_16x16x32_bf16 v[158:161], v[154:157], v[158:161], v[40:43]
	v_mfma_f32_16x16x32_bf16 v[162:165], v[154:157], v[162:165], v[32:35]
	v_mfma_f32_16x16x32_bf16 v[166:169], v[154:157], v[166:169], v[24:27]
	v_mfma_f32_16x16x32_bf16 v[170:173], v[154:157], v[170:173], v[16:19]
	s_nop 2
	ds_read_b128 v[16:19], v147 offset:40960
	ds_read_b128 v[24:27], v147 offset:43008
	ds_read_b128 v[32:35], v147 offset:45056
	ds_read_b128 v[40:43], v147 offset:47104
	s_waitcnt lgkmcnt(0)
	v_mfma_f32_16x16x32_bf16 v[100:103], v[128:131], v[16:19], v[100:103]
	v_mfma_f32_16x16x32_bf16 v[92:95], v[128:131], v[24:27], v[92:95]
	v_mfma_f32_16x16x32_bf16 v[192:195], v[128:131], v[32:35], v[84:87]
	v_mfma_f32_16x16x32_bf16 v[76:79], v[128:131], v[40:43], v[76:79]
	v_mfma_f32_16x16x32_bf16 v[68:71], v[132:135], v[16:19], v[68:71]
	v_mfma_f32_16x16x32_bf16 v[60:63], v[132:135], v[24:27], v[60:63]
	v_mfma_f32_16x16x32_bf16 v[128:131], v[132:135], v[32:35], v[52:55]
	v_mfma_f32_16x16x32_bf16 v[44:47], v[132:135], v[40:43], v[44:47]
	v_mfma_f32_16x16x32_bf16 v[132:135], v[150:153], v[16:19], v[36:39]
	v_mfma_f32_16x16x32_bf16 v[198:201], v[150:153], v[24:27], v[28:31]
	v_mfma_f32_16x16x32_bf16 v[204:207], v[150:153], v[32:35], v[20:23]
	v_mfma_f32_16x16x32_bf16 v[148:151], v[150:153], v[40:43], v[12:15]
	v_mfma_f32_16x16x32_bf16 v[208:211], v[154:157], v[16:19], v[8:11]
	v_mfma_f32_16x16x32_bf16 v[212:215], v[154:157], v[24:27], v[4:7]
	v_mfma_f32_16x16x32_bf16 v[216:219], v[154:157], v[32:35], v[0:3]
	v_mfma_f32_16x16x32_bf16 v[154:157], v[154:157], v[40:43], v[108:111]
	s_nop 1
	v_add_u32_e32 v0, v136, v146
	v_add_u32_e32 v136, v137, v146
	ds_read_b128 v[108:111], v0
	ds_read_b128 v[220:223], v0 offset:2048
	ds_read_b128 v[224:227], v0 offset:4096
	ds_read_b128 v[228:231], v0 offset:6144
	ds_read_b128 v[0:3], v136 offset:32768
	ds_read_b128 v[4:7], v136 offset:34816
	ds_read_b128 v[232:235], v136 offset:36864
	ds_read_b128 v[236:239], v136 offset:38912
	s_waitcnt lgkmcnt(0)
	v_mfma_f32_16x16x32_bf16 v[88:91], v[108:111], v[0:3], v[124:127]
	v_mfma_f32_16x16x32_bf16 v[96:99], v[108:111], v[4:7], v[120:123]
	v_mfma_f32_16x16x32_bf16 v[80:83], v[108:111], v[232:235], v[116:119]
	v_mfma_f32_16x16x32_bf16 v[84:87], v[108:111], v[236:239], v[112:115]
	v_mfma_f32_16x16x32_bf16 v[40:43], v[220:223], v[0:3], v[104:107]
	v_mfma_f32_16x16x32_bf16 v[52:55], v[220:223], v[4:7], v[178:181]
	v_mfma_f32_16x16x32_bf16 v[32:35], v[220:223], v[232:235], v[182:185]
	v_mfma_f32_16x16x32_bf16 v[36:39], v[220:223], v[236:239], v[186:189]
	v_mfma_f32_16x16x32_bf16 v[24:27], v[224:227], v[0:3], v[72:75]
	v_mfma_f32_16x16x32_bf16 v[28:31], v[224:227], v[4:7], v[64:67]
	v_mfma_f32_16x16x32_bf16 v[16:19], v[224:227], v[232:235], v[56:59]
	v_mfma_f32_16x16x32_bf16 v[20:23], v[224:227], v[236:239], v[48:51]
	v_mfma_f32_16x16x32_bf16 v[8:11], v[228:231], v[0:3], v[158:161]
	v_mfma_f32_16x16x32_bf16 v[12:15], v[228:231], v[4:7], v[162:165]
	v_mfma_f32_16x16x32_bf16 v[0:3], v[228:231], v[232:235], v[166:169]
	v_mfma_f32_16x16x32_bf16 v[4:7], v[228:231], v[236:239], v[170:173]
	ds_read_b128 v[48:51], v136 offset:40960
	ds_read_b128 v[64:67], v136 offset:43008
	ds_read_b128 v[158:161], v136 offset:45056
	ds_read_b128 v[162:165], v136 offset:47104
	s_waitcnt lgkmcnt(0)
	v_mfma_f32_16x16x32_bf16 v[104:107], v[220:223], v[48:51], v[68:71]
	v_cmp_ne_u32_e32 vcc, 0, v138
	v_cmp_eq_u32_e64 s[2:3], 0, v138
	s_waitcnt vmcnt(0)
	v_lshl_or_b32 v68, v140, 2, v141
	v_lshl_add_u32 v69, v139, 2, 0
	v_mfma_f32_16x16x32_bf16 v[120:123], v[108:111], v[48:51], v[100:103]
	v_lshl_add_u32 v152, v68, 9, v69
	v_add_u32_e32 v153, 0x400, v152
	v_add_u32_e32 v147, 0x6000, v152
	v_mfma_f32_16x16x32_bf16 v[124:127], v[108:111], v[64:67], v[92:95]
	v_add_u32_e32 v146, 0x6400, v152
	s_barrier
	v_mfma_f32_16x16x32_bf16 v[112:115], v[108:111], v[158:161], v[192:195]
	v_mfma_f32_16x16x32_bf16 v[116:119], v[108:111], v[162:165], v[76:79]
	v_mfma_f32_16x16x32_bf16 v[108:111], v[220:223], v[64:67], v[60:63]
	v_mfma_f32_16x16x32_bf16 v[92:95], v[220:223], v[158:161], v[128:131]
	v_mfma_f32_16x16x32_bf16 v[100:103], v[220:223], v[162:165], v[44:47]
	v_mfma_f32_16x16x32_bf16 v[56:59], v[224:227], v[48:51], v[132:135]
	v_mfma_f32_16x16x32_bf16 v[60:63], v[224:227], v[64:67], v[198:201]
	v_mfma_f32_16x16x32_bf16 v[44:47], v[224:227], v[158:161], v[204:207]
	v_mfma_f32_16x16x32_bf16 v[72:75], v[224:227], v[162:165], v[148:151]
	v_mfma_f32_16x16x32_bf16 v[48:51], v[228:231], v[48:51], v[208:211]
	s_nop 1
	v_add_u32_e32 v151, 0x2000, v152
	v_add_u32_e32 v150, 0x2400, v152
	v_add_u32_e32 v149, 0x4000, v152
	v_mfma_f32_16x16x32_bf16 v[64:67], v[228:231], v[64:67], v[212:215]
	v_add_u32_e32 v148, 0x4400, v152
	v_mfma_f32_16x16x32_bf16 v[68:71], v[228:231], v[158:161], v[216:219]
	v_mfma_f32_16x16x32_bf16 v[76:79], v[228:231], v[162:165], v[154:157]
	s_and_saveexec_b64 s[10:11], s[2:3]
	s_cbranch_execz .LBB0_1146
	ds_write2_b32 v152, v88, v96 offset1:16
	ds_write2_b32 v152, v89, v97 offset0:128 offset1:144
	ds_write2_b32 v153, v90, v98 offset1:16
	ds_write2_b32 v153, v91, v99 offset0:128 offset1:144
	ds_write2_b32 v152, v80, v84 offset0:32 offset1:48
	ds_write2_b32 v152, v81, v85 offset0:160 offset1:176
	ds_write2_b32 v153, v82, v86 offset0:32 offset1:48
	ds_write2_b32 v153, v83, v87 offset0:160 offset1:176
	ds_write2_b32 v152, v120, v124 offset0:64 offset1:80
	ds_write2_b32 v152, v121, v125 offset0:192 offset1:208
	ds_write2_b32 v153, v122, v126 offset0:64 offset1:80
	ds_write2_b32 v153, v123, v127 offset0:192 offset1:208
	ds_write2_b32 v152, v112, v116 offset0:96 offset1:112
	ds_write2_b32 v152, v113, v117 offset0:224 offset1:240
	ds_write2_b32 v153, v114, v118 offset0:96 offset1:112
	ds_write2_b32 v153, v115, v119 offset0:224 offset1:240
	ds_write2_b32 v151, v40, v52 offset1:16
	ds_write2_b32 v151, v41, v53 offset0:128 offset1:144
	ds_write2_b32 v150, v42, v54 offset1:16
	ds_write2_b32 v150, v43, v55 offset0:128 offset1:144
	ds_write2_b32 v151, v32, v36 offset0:32 offset1:48
	ds_write2_b32 v151, v33, v37 offset0:160 offset1:176
	ds_write2_b32 v150, v34, v38 offset0:32 offset1:48
	ds_write2_b32 v150, v35, v39 offset0:160 offset1:176
	ds_write2_b32 v151, v104, v108 offset0:64 offset1:80
	ds_write2_b32 v151, v105, v109 offset0:192 offset1:208
	ds_write2_b32 v150, v106, v110 offset0:64 offset1:80
	ds_write2_b32 v150, v107, v111 offset0:192 offset1:208
	ds_write2_b32 v151, v92, v100 offset0:96 offset1:112
	ds_write2_b32 v151, v93, v101 offset0:224 offset1:240
	ds_write2_b32 v150, v94, v102 offset0:96 offset1:112
	ds_write2_b32 v150, v95, v103 offset0:224 offset1:240
	ds_write2_b32 v149, v24, v28 offset1:16
	ds_write2_b32 v149, v25, v29 offset0:128 offset1:144
	ds_write2_b32 v148, v26, v30 offset1:16
	ds_write2_b32 v148, v27, v31 offset0:128 offset1:144
	ds_write2_b32 v149, v16, v20 offset0:32 offset1:48
	ds_write2_b32 v149, v17, v21 offset0:160 offset1:176
	ds_write2_b32 v148, v18, v22 offset0:32 offset1:48
	ds_write2_b32 v148, v19, v23 offset0:160 offset1:176
	ds_write2_b32 v149, v56, v60 offset0:64 offset1:80
	ds_write2_b32 v149, v57, v61 offset0:192 offset1:208
	ds_write2_b32 v148, v58, v62 offset0:64 offset1:80
	ds_write2_b32 v148, v59, v63 offset0:192 offset1:208
	ds_write2_b32 v149, v44, v72 offset0:96 offset1:112
	ds_write2_b32 v149, v45, v73 offset0:224 offset1:240
	ds_write2_b32 v148, v46, v74 offset0:96 offset1:112
	ds_write2_b32 v148, v47, v75 offset0:224 offset1:240
	ds_write2_b32 v147, v8, v12 offset1:16
	ds_write2_b32 v147, v9, v13 offset0:128 offset1:144
	ds_write2_b32 v146, v10, v14 offset1:16
	ds_write2_b32 v146, v11, v15 offset0:128 offset1:144
	ds_write2_b32 v147, v0, v4 offset0:32 offset1:48
	ds_write2_b32 v147, v1, v5 offset0:160 offset1:176
	ds_write2_b32 v146, v2, v6 offset0:32 offset1:48
	ds_write2_b32 v146, v3, v7 offset0:160 offset1:176
	ds_write2_b32 v147, v48, v64 offset0:64 offset1:80
	ds_write2_b32 v147, v49, v65 offset0:192 offset1:208
	ds_write2_b32 v146, v50, v66 offset0:64 offset1:80
	ds_write2_b32 v146, v51, v67 offset0:192 offset1:208
	ds_write2_b32 v147, v68, v76 offset0:96 offset1:112
	ds_write2_b32 v147, v69, v77 offset0:224 offset1:240
	ds_write2_b32 v146, v70, v78 offset0:96 offset1:112
	ds_write2_b32 v146, v71, v79 offset0:224 offset1:240

	.amdhsa_kernel _Z14fwd_megakernel6Params
		.amdhsa_group_segment_fixed_size 0
		.amdhsa_private_segment_fixed_size 0
		.amdhsa_kernarg_size 504
		.amdhsa_user_sgpr_count 2
		.amdhsa_user_sgpr_dispatch_ptr 0
		.amdhsa_user_sgpr_queue_ptr 0
		.amdhsa_user_sgpr_kernarg_segment_ptr 1
		.amdhsa_user_sgpr_dispatch_id 0
		.amdhsa_user_sgpr_kernarg_preload_length 0
		.amdhsa_user_sgpr_kernarg_preload_offset 0
		.amdhsa_user_sgpr_private_segment_size 0
		.amdhsa_uses_dynamic_stack 0
		.amdhsa_enable_private_segment 0
		.amdhsa_system_sgpr_workgroup_id_x 1
		.amdhsa_system_sgpr_workgroup_id_y 0
		.amdhsa_system_sgpr_workgroup_id_z 0
		.amdhsa_system_sgpr_workgroup_info 0
		.amdhsa_system_vgpr_workitem_id 2
		.amdhsa_next_free_vgpr 256
		.amdhsa_next_free_sgpr 102
		.amdhsa_accum_offset 256
		.amdhsa_reserve_vcc 1
		.amdhsa_float_round_mode_32 0
		.amdhsa_float_round_mode_16_64 0
		.amdhsa_float_denorm_mode_32 3
		.amdhsa_float_denorm_mode_16_64 3
		.amdhsa_dx10_clamp 1
		.amdhsa_ieee_mode 1
		.amdhsa_fp16_overflow 0
		.amdhsa_tg_split 0
		.amdhsa_exception_fp_ieee_invalid_op 0
		.amdhsa_exception_fp_denorm_src 0
		.amdhsa_exception_fp_ieee_div_zero 0
		.amdhsa_exception_fp_ieee_overflow 0
		.amdhsa_exception_fp_ieee_underflow 0
		.amdhsa_exception_fp_ieee_inexact 0
		.amdhsa_exception_int_div_zero 0
	.end_amdhsa_kernel

amdhsa.kernels:
  - .agpr_count:     0
    .args:
      - .offset:         0
        .size:           248
        .value_kind:     by_value
      - .offset:         248
        .size:           4
        .value_kind:     hidden_block_count_x
      - .offset:         252
        .size:           4
        .value_kind:     hidden_block_count_y
      - .offset:         256
        .size:           4
        .value_kind:     hidden_block_count_z
      - .offset:         260
        .size:           2
        .value_kind:     hidden_group_size_x
      - .offset:         262
        .size:           2
        .value_kind:     hidden_group_size_y
      - .offset:         264
        .size:           2
        .value_kind:     hidden_group_size_z
      - .offset:         266
        .size:           2
        .value_kind:     hidden_remainder_x
      - .offset:         268
        .size:           2
        .value_kind:     hidden_remainder_y
      - .offset:         270
        .size:           2
        .value_kind:     hidden_remainder_z
      - .offset:         288
        .size:           8
        .value_kind:     hidden_global_offset_x
      - .offset:         296
        .size:           8
        .value_kind:     hidden_global_offset_y
      - .offset:         304
        .size:           8
        .value_kind:     hidden_global_offset_z
      - .offset:         312
        .size:           2
        .value_kind:     hidden_grid_dims
      - .offset:         336
        .size:           8
        .value_kind:     hidden_multigrid_sync_arg
      - .offset:         368
        .size:           4
        .value_kind:     hidden_dynamic_lds_size
    .group_segment_fixed_size: 0
    .kernarg_segment_align: 8
    .kernarg_segment_size: 504
    .language:       OpenCL C
    .language_version:
      - 2
      - 0
    .max_flat_workgroup_size: 512
    .name:           _Z14fwd_megakernel6Params
    .private_segment_fixed_size: 0
    .sgpr_count:     108
    .sgpr_spill_count: 33
    .symbol:         _Z14fwd_megakernel6Params.kd
    .uniform_work_group_size: 1
    .uses_dynamic_stack: false
    .vgpr_count:     256
    .vgpr_spill_count: 0
    .wavefront_size: 64
